# EpiConv v4: first half's PS rows loaded at tile start (hidden behind the K-loop), ws-derived bases computed once per phase
# speedup vs baseline: 1.0029x; 1.0029x over previous
; __device__ __forceinline__ int fresh_tid(int wave) { int z = 0; asm volatile("" : "+v"(z)); return wave * 64 + (int)__builtin_amdgcn_mbcnt_hi(~0u, __builtin_amdgcn_mbcnt_lo(~0u, (unsigned)z)); }
; template <class Epi, bool HALO>
; __device__ __forceinline__ void gemm_phase(LAS unsigned char* lds, const bf16_t* Ag, const bf16_t* Btg, const int K, const int nM, const int nN, const int G, const int cidx, const int wave_, const Epi& E) {
;     int tid_ = fresh_tid(wave_); asm volatile("" : "+v"(tid_));
;     const int tid = tid_, wid = __builtin_amdgcn_readfirstlane(tid >> 6), lane = tid & 63, wr = wid >> 2, wc = wid & 3, fr = lane & 15, fq = lane >> 4;
;     const int nt = K / BK;
;     StaticOrder S; S.init(nM, nN, G, cidx);
;     unsigned voffA[2], voffB[2];
; #pragma unroll
;     for (int i = 0; i < 2; ++i) { int R, C; stage_rc(tid * 16 + i * 8192, R, C); const int Rb = (R & ~31) + perm32(R & 31);
;         const int Ra = HALO ? (R - 2 * (R >> 6)) : R;
;         voffA[i] = (unsigned)(Ra * K + C) * 2u; voffB[i] = (unsigned)(Rb * K + C) * 2u; }
;     const size_t kstep = (size_t)(BK * 2);
;     const size_t hstepB = (size_t)HALF * K * 2;
;     const size_t hstepA = HALO ? (size_t)124 * K * 2 : hstepB;
;     const unsigned ldsw = (unsigned)wid * 1024u;
;     const int aoff = lds_byte(wr * 64 + fr, fq * 8), boff = lds_byte(wc * 32 + fr, fq * 8);
;     ...
;     auto halo_row0 = [](int pm) -> long { int sb, t0, sl; halo_decode(pm, sb, t0, sl); return (long)sb + t0 - 1; };
;     Unit cur, nxt; int ui = 0;
;     if (!S.next(0, cur)) return;
;     f32x4 acc[2][2][4][2];
; #pragma unroll
;     for (int a = 0; a < 2; ++a)
; #pragma unroll
;         for (int b = 0; b < 2; ++b)
; #pragma unroll
;             for (int m = 0; m < 4; ++m)
; #pragma unroll
;                 for (int n = 0; n < 2; ++n) acc[a][b][m][n] = (f32x4){0.f, 0.f, 0.f, 0.f};
;     bf16x8 At[4][2], B0[2][2], B1[2][2];
;     const char* cA = PG8_ABASE(cur.pm); const char* cB = PG8_BBASE(cur.pn);
;     PG8_STAGE(PG8_SB(0, 0), cB, voffB); PG8_STAGE(PG8_SB(0, 1), cB + hstepB, voffB); PG8_STAGE(PG8_SA(0, 0), cA, voffA); PG8_STAGE(PG8_SA(0, 1), cA + hstepA, voffA);
;     if (wr == 1) PG8_BAR;
;     PG8_WAIT_V(2); PG8_BAR;
;     PG8_STAGE(PG8_SB(1, 0), cB + kstep, voffB); PG8_STAGE(PG8_SA(1, 0), cA + kstep, voffA); PG8_STAGE(PG8_SB(1, 1), cB + hstepB + kstep, voffB);
;     PG8_WAIT_V(6); PG8_BAR;
.LBB0_772:
	s_or_b64 exec, exec, s[2:3]
	v_readlane_b32 s2, v254, 0
	v_readlane_b32 s3, v254, 1
	s_waitcnt lgkmcnt(0)
	v_mov_b32_e32 v0, v145
	s_barrier
	v_readlane_b32 s64, v254, 0
	v_readlane_b32 s65, v254, 1
	v_readlane_b32 s66, v255, 4
	s_nop 2
	s_load_dwordx2 s[98:99], s[64:65], 0xe0
	s_mul_i32 s66, s66, 0x16000
	s_bfe_u32 s32, s81, 0x20006
	s_waitcnt lgkmcnt(0)
	s_add_u32 s70, s98, 0x3600000
	s_addc_u32 s71, s99, 0
	s_lshl_b32 s92, s32, 10
	s_add_i32 s92, s92, s66
	s_add_i32 s92, s92, 0x3500000
	s_add_u32 s100, s98, s92
	s_addc_u32 s101, s99, 0
	s_lshl_b32 s92, s32, 6
	s_add_i32 s92, s92, 0xf400000
	s_add_u32 s98, s98, s92
	s_addc_u32 s99, s99, 0
	v_readlane_b32 s0, v254, 17
	v_mbcnt_lo_u32_b32 v0, -1, v0
	v_mbcnt_hi_u32_b32 v0, -1, v0
	v_add_u32_e32 v9, s81, v0
	v_readlane_b32 s1, v254, 18
	s_andn2_b64 vcc, exec, s[0:1]
	v_readfirstlane_b32 s4, v9
	s_cbranch_vccnz .LBB0_814
	v_lshlrev_b32_e32 v0, 4, v9
	v_add_u32_e32 v1, 0x2000, v0
	v_ashrrev_i32_e32 v2, 31, v1
	v_lshrrev_b32_e32 v2, 22, v2
	v_add_u32_e32 v2, v1, v2
	v_ashrrev_i32_e32 v8, 10, v2
	s_load_dwordx2 s[12:13], s[2:3], 0xe0
	v_mul_i32_i24_e32 v2, 0x400, v8
	v_sub_u32_e32 v1, v1, v2
	v_lshrrev_b32_e32 v2, 4, v1
	v_bitop3_b32 v1, v2, v1, 32 bitop3:0x6c
	v_ashrrev_i32_e32 v2, 31, v1
	s_waitcnt lgkmcnt(0)
	s_add_u32 s0, s12, 0x4100000
	v_lshrrev_b32_e32 v2, 26, v2
	s_addc_u32 s1, s13, 0
	v_readlane_b32 s2, v255, 6
	v_add_u32_e32 v2, v1, v2
	v_lshlrev_b32_e32 v4, 3, v8
	s_add_u32 s2, s12, s2
	v_ashrrev_i32_e32 v3, 6, v2
	v_and_b32_e32 v4, -16, v4
	s_addc_u32 s3, s13, 0
	v_add_u32_e32 v4, v3, v4
	s_add_u32 s38, s2, 0x700000
	v_and_b32_e32 v3, 3, v3
	s_mov_b32 s2, 0x1fffe0
	v_lshrrev_b32_e32 v5, 2, v4
	v_lshlrev_b32_e32 v6, 1, v4
	v_and_b32_e32 v2, 0xc0, v2
	v_and_or_b32 v3, v4, s2, v3
	v_and_b32_e32 v5, 4, v5
	v_and_b32_e32 v6, 24, v6
	v_sub_u32_e32 v1, v1, v2
	v_lshrrev_b32_e32 v2, 5, v4
	v_or3_b32 v3, v3, v5, v6
	v_lshlrev_b32_e32 v5, 5, v8
	v_ashrrev_i16_sdwa v1, v184, sext(v1) dst_sel:DWORD dst_unused:UNUSED_PAD src0_sel:DWORD src1_sel:BYTE_0
	v_and_b32_e32 v2, 0x1ffffe, v2
	v_and_b32_e32 v5, 32, v5
	v_bfe_i32 v10, v1, 0, 16
	v_and_b32_e32 v250, 15, v4
	v_bfe_u32 v251, v4, 4, 2
	v_lshl_or_b32 v250, v250, 2, v251
	v_and_b32_e32 v251, 0xffffffc0, v4
	v_or_b32_e32 v250, v250, v251
	v_sub_u32_e32 v2, v250, v2
	v_add_lshl_u32 v1, v5, v10, 1
	v_lshlrev_b32_e32 v11, 11, v2
	v_lshl_add_u32 v152, v3, 11, v1
	v_add_u32_e32 v154, v11, v1
	v_bfe_i32 v1, v9, 27, 1
	v_lshrrev_b32_e32 v1, 22, v1
	v_add_u32_e32 v1, v0, v1
	v_and_b32_e32 v1, 0xfffffc00, v1
	v_sub_u32_e32 v0, v0, v1
	v_lshrrev_b32_e32 v1, 4, v0
	v_ashrrev_i32_e32 v3, 31, v9
	v_bitop3_b32 v0, v1, v0, 32 bitop3:0x6c
	v_lshrrev_b32_e32 v3, 26, v3
	v_ashrrev_i32_e32 v1, 31, v0
	v_add_u32_e32 v3, v9, v3
	v_lshrrev_b32_e32 v1, 26, v1
	v_ashrrev_i32_e32 v12, 6, v3
	v_add_u32_e32 v1, v0, v1
	v_lshlrev_b32_e32 v3, 3, v12
	v_ashrrev_i32_e32 v2, 6, v1
	v_and_b32_e32 v3, -16, v3
	v_add_u32_e32 v3, v2, v3
	v_and_b32_e32 v2, 3, v2
	v_lshrrev_b32_e32 v4, 2, v3
	v_lshlrev_b32_e32 v5, 1, v3
	v_and_b32_e32 v1, 0xc0, v1
	s_addc_u32 s39, s3, 0
	s_ashr_i32 s5, s4, 6
	v_and_or_b32 v2, v3, s2, v2
	v_and_b32_e32 v4, 4, v4
	v_and_b32_e32 v5, 24, v5
	v_sub_u32_e32 v0, v0, v1
	s_ashr_i32 s8, s4, 8
	s_lshl_b32 s40, s5, 10
	v_or3_b32 v2, v2, v4, v5
	v_lshlrev_b32_e32 v4, 5, v12
	v_ashrrev_i16_sdwa v0, v184, sext(v0) dst_sel:DWORD dst_unused:UNUSED_PAD src0_sel:DWORD src1_sel:BYTE_0
	v_readlane_b32 s2, v254, 28
	v_and_b32_e32 v4, 32, v4
	v_bfe_i32 v13, v0, 0, 16
	v_readlane_b32 s3, v254, 29
	s_add_u32 s18, s38, s2
	v_add_lshl_u32 v0, v4, v13, 1
	s_addc_u32 s19, s39, s3
	s_add_i32 s41, s40, 0
	v_lshl_add_u32 v156, v2, 11, v0
	s_add_i32 m0, s41, 0x10000
	v_lshrrev_b32_e32 v1, 5, v3
	global_load_lds_dwordx4 v156, s[18:19]
	s_add_i32 m0, s41, 0x12000
	s_add_u32 s2, s18, 0x40000
	global_load_lds_dwordx4 v152, s[18:19]
	s_addc_u32 s3, s19, 0
	s_add_i32 m0, s41, 0x14000
	v_and_b32_e32 v1, 0x1ffffe, v1
	global_load_lds_dwordx4 v156, s[2:3]
	s_add_i32 m0, s41, 0x16000
	v_and_b32_e32 v250, 15, v3
	v_bfe_u32 v251, v3, 4, 2
	v_lshl_or_b32 v250, v250, 2, v251
	v_and_b32_e32 v251, 0xffffffc0, v3
	v_or_b32_e32 v250, v250, v251
	v_sub_u32_e32 v1, v250, v1
	global_load_lds_dwordx4 v152, s[2:3]
	v_readlane_b32 s2, v254, 43
	s_add_u32 s2, s0, s2
	v_readlane_b32 s3, v254, 44
	v_lshlrev_b32_e32 v14, 11, v1
	s_addc_u32 s3, s1, s3
	s_add_i32 s42, s41, 0x2000
	v_add_u32_e32 v158, v14, v0
	s_mov_b32 m0, s41
	s_add_u32 s6, s2, 0x3e000
	global_load_lds_dwordx4 v158, s[2:3]
	s_mov_b32 m0, s42
	s_addc_u32 s7, s3, 0
	s_add_i32 s43, s41, 0x4000
	global_load_lds_dwordx4 v154, s[2:3]
	s_mov_b32 m0, s43
	s_add_i32 s44, s41, 0x6000
	global_load_lds_dwordx4 v158, s[6:7]
	s_mov_b32 m0, s44
	v_mov_b32_e32 v157, v145
	global_load_lds_dwordx4 v154, s[6:7]
	v_mov_b32_e32 v153, v145
	v_mov_b32_e32 v159, v145
	v_mov_b32_e32 v155, v145
	s_cmp_eq_u32 s8, 1
	v_lshl_add_u64 v[6:7], s[18:19], 0, v[156:157]
	v_lshl_add_u64 v[4:5], s[18:19], 0, v[152:153]
	v_lshl_add_u64 v[0:1], s[2:3], 0, v[158:159]
	s_cselect_b64 s[22:23], -1, 0
	s_cmp_lg_u32 s8, 1
	v_lshl_add_u64 v[2:3], s[2:3], 0, v[154:155]
	s_cbranch_scc1 .LBB0_775
	s_barrier

; __device__ __forceinline__ void halo_decode(int pm, int& seqbase, int& t0, int& slen) {
;     if (pm < NBATCH * HT_P) { const int s = pm / HT_P, j = pm - s * HT_P; seqbase = s * SP; t0 = 248 * j; slen = SP; }
;     else { const int q = pm - NBATCH * HT_P, s = q / HT_S, j = q - s * HT_S; seqbase = MP + s * SS; t0 = 248 * j; slen = SS; }
; }
; template <class Epi, bool HALO>
; __device__ __forceinline__ void gemm_phase(LAS unsigned char* lds, const bf16_t* Ag, const bf16_t* Btg, const int K, const int nM, const int nN, const int G, const int cidx, const int wave_, const Epi& E) {
;     ...
;     auto halo_row0 = [](int pm) -> long { int sb, t0, sl; halo_decode(pm, sb, t0, sl); return (long)sb + t0 - 1; };
.LBB0_785:
	s_mul_i32 s20, s29, 0xf8
	s_ashr_i32 s21, s30, 31
	s_ashr_i32 s29, s20, 31
	s_add_u32 s20, s30, s20
	s_addc_u32 s21, s21, s29
	s_lshl_b64 s[20:21], s[20:21], 11
	s_add_u32 s20, s0, s20
	s_addc_u32 s21, s1, s21
	s_add_u32 s30, s20, 0xfffff800
	s_addc_u32 s31, s21, -1
.LBB0_786:
	s_cmpk_gt_i32 s36, 0x10f
	s_cbranch_scc1 EC2_smp
	s_mul_hi_i32 s86, s36, 0x78787879
	s_lshr_b32 s87, s86, 31
	s_ashr_i32 s86, s86, 4
	s_add_i32 s86, s86, s87
	s_lshl_b32 s88, s86, 13
	s_mul_i32 s86, s86, 34
	s_sub_i32 s86, s36, s86
	s_movk_i32 s91, 0x2000
	s_branch EC2_join

; template <class Epi, bool HALO>
; __device__ __forceinline__ void gemm_phase(LAS unsigned char* lds, const bf16_t* Ag, const bf16_t* Btg, const int K, const int nM, const int nN, const int G, const int cidx, const int wave_, const Epi& E) {
;     ...
;     f32x4 acc[2][2][4][2];
; #pragma unroll
;     for (int a = 0; a < 2; ++a)
; #pragma unroll
;         for (int b = 0; b < 2; ++b)
; #pragma unroll
;             for (int m = 0; m < 4; ++m)
; #pragma unroll
;                 for (int n = 0; n < 2; ++n) acc[a][b][m][n] = (f32x4){0.f, 0.f, 0.f, 0.f};
;     __device__ __forceinline__ void operator()(const f32x4 (&acc)[2][2][4][2], const Unit& u, int wr, int wc, int fr, int fq) const {
;     ...
;             const int tbase = t0 + 62 * (2 * ai + wr) - 1;
;             float rs[4];
; #pragma unroll
;             for (int m = 0; m < 4; ++m) { const int t = tbase + 16 * m + fr; const bool vin = (t >= 0) && (t < slen); const int grow = seqbase + (vin ? t : 0);
;                 const f32x4 p = *(const f32x4*)(PS + (size_t)grow * 16 + 4 * fq); float s = (p[0] + p[1]) + (p[2] + p[3]); s = bfly_add<16>(s); s = bfly_add<32>(s); rs[m] = vin ? rsqrtf(s * (1.f / DM) + EPS) : 0.f; }
EC2_join:
	s_mul_i32 s86, s86, 0xf8
	s_bfe_u32 s89, s81, 0x10008
	s_mul_i32 s89, s89, 62
	s_add_i32 s89, s89, s86
	s_add_i32 s89, s89, -1
	v_mbcnt_lo_u32_b32 v176, -1, 0
	v_mbcnt_hi_u32_b32 v176, -1, v176
	v_and_b32_e32 v164, 15, v176
	v_lshlrev_b32_e32 v164, 2, v164
	v_bfe_u32 v165, v176, 4, 2
	v_lshlrev_b32_e32 v172, 8, v165
	v_lshlrev_b32_e32 v165, 4, v165
	v_add_u32_e32 v174, s89, v164
	v_add_u32_e32 v176, 0, v174
	v_cmp_gt_u32_e32 vcc, s91, v176
	s_nop 1
	v_cndmask_b32_e32 v176, 0, v176, vcc
	v_add_u32_e32 v176, s88, v176
	v_lshl_add_u32 v252, v176, 6, v165
	global_load_dwordx4 v[240:243], v252, s[70:71]
	v_add_u32_e32 v176, 1, v174
	v_cmp_gt_u32_e32 vcc, s91, v176
	s_nop 1
	v_cndmask_b32_e32 v176, 0, v176, vcc
	v_add_u32_e32 v176, s88, v176
	v_lshl_add_u32 v253, v176, 6, v165
	global_load_dwordx4 v[244:247], v253, s[70:71]
	v_add_u32_e32 v176, 2, v174
	v_cmp_gt_u32_e32 vcc, s91, v176
	s_nop 1
	v_cndmask_b32_e32 v176, 0, v176, vcc
	v_add_u32_e32 v176, s88, v176
	v_lshl_add_u32 v252, v176, 6, v165
	global_load_dwordx4 v[248:251], v252, s[70:71]
	v_add_u32_e32 v176, 3, v174
	v_cmp_gt_u32_e32 vcc, s91, v176
	s_nop 1
	v_cndmask_b32_e32 v176, 0, v176, vcc
	v_add_u32_e32 v176, s88, v176
	v_lshl_add_u32 v253, v176, 6, v165
	global_load_dwordx4 v[160:163], v253, s[70:71]
	s_ashr_i32 s29, s28, 31
	s_lshl_b64 s[20:21], s[28:29], 19
	s_add_u32 s34, s38, s20
	s_addc_u32 s35, s39, s21
	s_and_b64 s[14:15], s[14:15], exec
	s_cselect_b32 s20, s35, s19
	s_cselect_b32 s21, s34, s18
	s_add_u32 s2, s2, 0x3e080
	s_addc_u32 s3, s3, 0
	s_add_u32 s29, s18, 0x100
	v_mov_b32_e32 v0, 0
	s_addc_u32 s37, s19, 0
	s_mov_b32 s51, -2
	v_mov_b32_e32 v1, v0
	v_mov_b32_e32 v2, v0
	v_mov_b32_e32 v3, v0
	v_mov_b32_e32 v32, v0
	v_mov_b32_e32 v33, v0
	v_mov_b32_e32 v34, v0
	v_mov_b32_e32 v35, v0
	v_mov_b32_e32 v4, v0
	v_mov_b32_e32 v5, v0
	v_mov_b32_e32 v6, v0
	v_mov_b32_e32 v7, v0
	v_mov_b32_e32 v36, v0
	v_mov_b32_e32 v37, v0
	v_mov_b32_e32 v38, v0
	v_mov_b32_e32 v39, v0
	v_mov_b32_e32 v8, v0
	v_mov_b32_e32 v9, v0
	v_mov_b32_e32 v10, v0
	v_mov_b32_e32 v11, v0
	v_mov_b32_e32 v40, v0
	v_mov_b32_e32 v41, v0
	v_mov_b32_e32 v42, v0
	v_mov_b32_e32 v43, v0
	v_mov_b32_e32 v12, v0
	v_mov_b32_e32 v13, v0
	v_mov_b32_e32 v14, v0
	v_mov_b32_e32 v15, v0
	v_mov_b32_e32 v44, v0
	v_mov_b32_e32 v45, v0
	v_mov_b32_e32 v46, v0
	v_mov_b32_e32 v47, v0
	v_mov_b32_e32 v16, v0
	v_mov_b32_e32 v17, v0
	v_mov_b32_e32 v18, v0
	v_mov_b32_e32 v19, v0
	v_mov_b32_e32 v48, v0
	v_mov_b32_e32 v49, v0
	v_mov_b32_e32 v50, v0
	v_mov_b32_e32 v51, v0
	v_mov_b32_e32 v20, v0
	v_mov_b32_e32 v21, v0
	v_mov_b32_e32 v22, v0
	v_mov_b32_e32 v23, v0
	v_mov_b32_e32 v52, v0
	v_mov_b32_e32 v53, v0
	v_mov_b32_e32 v54, v0
	v_mov_b32_e32 v55, v0
	v_mov_b32_e32 v24, v0
	v_mov_b32_e32 v25, v0
	v_mov_b32_e32 v26, v0
	v_mov_b32_e32 v27, v0
	v_mov_b32_e32 v56, v0
	v_mov_b32_e32 v57, v0
	v_mov_b32_e32 v58, v0
	v_mov_b32_e32 v59, v0
	v_mov_b32_e32 v28, v0
	v_mov_b32_e32 v29, v0
	v_mov_b32_e32 v30, v0
	v_mov_b32_e32 v31, v0
	v_mov_b32_e32 v60, v0
	v_mov_b32_e32 v61, v0
	v_mov_b32_e32 v62, v0
	v_mov_b32_e32 v63, v0
	v_mov_b32_e32 v64, v0
	v_mov_b32_e32 v65, v0
	v_mov_b32_e32 v66, v0
	v_mov_b32_e32 v67, v0
	v_mov_b32_e32 v96, v0
	v_mov_b32_e32 v97, v0
	v_mov_b32_e32 v98, v0
	v_mov_b32_e32 v99, v0
	v_mov_b32_e32 v68, v0
	v_mov_b32_e32 v69, v0
	v_mov_b32_e32 v70, v0
	v_mov_b32_e32 v71, v0
	v_mov_b32_e32 v100, v0
	v_mov_b32_e32 v101, v0
	v_mov_b32_e32 v102, v0
	v_mov_b32_e32 v103, v0
	v_mov_b32_e32 v72, v0
	v_mov_b32_e32 v73, v0
	v_mov_b32_e32 v74, v0
	v_mov_b32_e32 v75, v0
	v_mov_b32_e32 v104, v0
	v_mov_b32_e32 v105, v0
	v_mov_b32_e32 v106, v0
	v_mov_b32_e32 v107, v0
	v_mov_b32_e32 v76, v0
	v_mov_b32_e32 v77, v0
	v_mov_b32_e32 v78, v0
	v_mov_b32_e32 v79, v0
	v_mov_b32_e32 v108, v0
	v_mov_b32_e32 v109, v0
	v_mov_b32_e32 v110, v0
	v_mov_b32_e32 v111, v0
	v_mov_b32_e32 v80, v0
	v_mov_b32_e32 v81, v0
	v_mov_b32_e32 v82, v0
	v_mov_b32_e32 v83, v0
	v_mov_b32_e32 v112, v0
	v_mov_b32_e32 v113, v0
	v_mov_b32_e32 v114, v0
	v_mov_b32_e32 v115, v0
	v_mov_b32_e32 v84, v0
	v_mov_b32_e32 v85, v0
	v_mov_b32_e32 v86, v0
	v_mov_b32_e32 v87, v0
	v_mov_b32_e32 v116, v0
	v_mov_b32_e32 v117, v0
	v_mov_b32_e32 v118, v0
	v_mov_b32_e32 v119, v0
	v_mov_b32_e32 v88, v0
	v_mov_b32_e32 v89, v0
	v_mov_b32_e32 v90, v0
	v_mov_b32_e32 v91, v0
	v_mov_b32_e32 v120, v0
	v_mov_b32_e32 v121, v0
	v_mov_b32_e32 v122, v0
	v_mov_b32_e32 v123, v0
	v_mov_b32_e32 v92, v0
	v_mov_b32_e32 v93, v0
	v_mov_b32_e32 v94, v0
	v_mov_b32_e32 v95, v0
	v_mov_b32_e32 v124, v0
	v_mov_b32_e32 v125, v0
	v_mov_b32_e32 v126, v0
	v_mov_b32_e32 v127, v0

;     __device__ __forceinline__ void operator()(const f32x4 (&acc)[2][2][4][2], const Unit& u, int wr, int wc, int fr, int fq) const {
;     ...
;         const f32x4* ct = (const f32x4*)(CT + (size_t)(128 * u.pn) * 8) + (32 * wc + 8 * fq) * 2;
;         const bool f0 = (fr == 0), f15 = (fr == 15);
; #pragma unroll
;         for (int ai = 0; ai < 2; ++ai) {
;             const int tbase = t0 + 62 * (2 * ai + wr) - 1;
;             float rs[4];
; #pragma unroll
;             for (int m = 0; m < 4; ++m) { const int t = tbase + 16 * m + fr; const bool vin = (t >= 0) && (t < slen); const int grow = seqbase + (vin ? t : 0);
;                 const f32x4 p = *(const f32x4*)(PS + (size_t)grow * 16 + 4 * fq); float s = (p[0] + p[1]) + (p[2] + p[3]); s = bfly_add<16>(s); s = bfly_add<32>(s); rs[m] = vin ? rsqrtf(s * (1.f / DM) + EPS) : 0.f; }
;             unsigned outw[4][2][2];
; #pragma unroll
;             for (int n = 0; n < 2; ++n)
; #pragma unroll
;                 for (int jp = 0; jp < 2; ++jp) {
;                     const int cidx = (4 * n + 2 * jp) * 2;
;                     const f32x4 c0a = ct[cidx], c0b = ct[cidx + 1], c1a = ct[cidx + 2], c1b = ct[cidx + 3];
;                     const f32x2 wv0 = {c0a[0], c1a[0]}, wv1 = {c0a[1], c1a[1]}, wv2 = {c0a[2], c1a[2]}, bv = {c0a[3], c1a[3]};
;                     const f32x2 wg0 = {c0b[0], c1b[0]}, wg1 = {c0b[1], c1b[1]}, wg2 = {c0b[2], c1b[2]}, bg = {c0b[3], c1b[3]};
;                     f32x2 uv[4], ug[4], cv[4];
; #pragma unroll
;                     for (int m = 0; m < 4; ++m) { uv[m] = (f32x2){acc[ai][0][m][n][2 * jp], acc[ai][0][m][n][2 * jp + 1]}; ug[m] = (f32x2){acc[ai][1][m][n][2 * jp], acc[ai][1][m][n][2 * jp + 1]}; }
;                     asm volatile("" : "+v"(uv[0]), "+v"(uv[1]), "+v"(uv[2]), "+v"(uv[3]), "+v"(ug[0]), "+v"(ug[1]), "+v"(ug[2]), "+v"(ug[3]));
;                     {
;                         f32x2 rv[4], lv[4];
; #pragma unroll
;                         for (int m = 0; m < 4; ++m) { uv[m] = uv[m] * rs[m]; rv[m] = (f32x2){dpp_ror1(uv[m][0]), dpp_ror1(uv[m][1])}; lv[m] = (f32x2){dpp_ror15(uv[m][0]), dpp_ror15(uv[m][1])}; }
; #pragma unroll
;                         for (int m = 0; m < 4; ++m) { const f32x2 pv_ = (m > 0 && f0) ? rv[m > 0 ? m - 1 : 0] : rv[m], nv_ = (m < 3 && f15) ? lv[m < 3 ? m + 1 : 3] : lv[m];
;                             cv[m] = bv + wv0 * pv_ + wv1 * uv[m] + wv2 * nv_; }
.LBB0_790:
	s_lshl_b32 s92, s33, 12
	s_add_u32 s64, s100, s92
	s_addc_u32 s65, s101, 0
	s_lshl_b32 s92, s33, 8
	s_add_u32 s86, s98, s92
	s_addc_u32 s87, s99, 0
	v_mov_b32_e32 v252, s78
	s_movk_i32 s54, 0x1600
	global_load_dwordx4 v[190:193], v172, s[64:65]
	global_load_dwordx4 v[194:197], v172, s[64:65] offset:16
	global_load_dwordx4 v[198:201], v172, s[64:65] offset:32
	global_load_dwordx4 v[202:205], v172, s[64:65] offset:48
	v_add_u32_e32 v176, 0, v174
	v_cmp_gt_u32_e64 s[52:53], s91, v176
	v_add_u32_e32 v176, 1, v174
	v_cmp_gt_u32_e64 s[2:3], s91, v176
	v_add_u32_e32 v176, 2, v174
	v_cmp_gt_u32_e64 s[18:19], s91, v176
	v_add_u32_e32 v176, 3, v174
	v_cmp_gt_u32_e64 s[32:33], s91, v176
	s_waitcnt vmcnt(4)
	v_add_f32_e32 v240, v240, v241
	v_add_f32_e32 v242, v242, v243
	v_add_f32_e32 v240, v240, v242
	v_mov_b32_e32 v241, v240
	s_nop 1
	v_permlane16_swap_b32_e32 v240, v241
	v_add_f32_e32 v240, v240, v241
	v_mov_b32_e32 v241, v240
	s_nop 1
	v_permlane32_swap_b32_e32 v240, v241
	v_add_f32_e32 v240, v240, v241
	v_fma_f32 v240, v240, s82, v252
	v_rsq_f32_e32 v240, v240
	s_nop 0
	v_cndmask_b32_e64 v178, 0, v240, s[52:53]
	s_waitcnt vmcnt(4)
	v_add_f32_e32 v244, v244, v245
	v_add_f32_e32 v246, v246, v247
	v_add_f32_e32 v244, v244, v246
	v_mov_b32_e32 v245, v244
	s_nop 1
	v_permlane16_swap_b32_e32 v244, v245
	v_add_f32_e32 v244, v244, v245
	v_mov_b32_e32 v245, v244
	s_nop 1
	v_permlane32_swap_b32_e32 v244, v245
	v_add_f32_e32 v244, v244, v245
	v_fma_f32 v244, v244, s82, v252
	v_rsq_f32_e32 v244, v244
	s_nop 0
	v_cndmask_b32_e64 v180, 0, v244, s[2:3]
	s_waitcnt vmcnt(4)
	v_add_f32_e32 v248, v248, v249
	v_add_f32_e32 v250, v250, v251
	v_add_f32_e32 v248, v248, v250
	v_mov_b32_e32 v249, v248
	s_nop 1
	v_permlane16_swap_b32_e32 v248, v249
	v_add_f32_e32 v248, v248, v249
	v_mov_b32_e32 v249, v248
	s_nop 1
	v_permlane32_swap_b32_e32 v248, v249
	v_add_f32_e32 v248, v248, v249
	v_fma_f32 v248, v248, s82, v252
	v_rsq_f32_e32 v248, v248
	s_nop 0
	v_cndmask_b32_e64 v182, 0, v248, s[18:19]
	s_waitcnt vmcnt(4)
	v_add_f32_e32 v160, v160, v161
	v_add_f32_e32 v162, v162, v163
	v_add_f32_e32 v160, v160, v162
	v_mov_b32_e32 v161, v160
	s_nop 1
	v_permlane16_swap_b32_e32 v160, v161
	v_add_f32_e32 v160, v160, v161
	v_mov_b32_e32 v161, v160
	s_nop 1
	v_permlane32_swap_b32_e32 v160, v161
	v_add_f32_e32 v160, v160, v161
	v_fma_f32 v160, v160, s82, v252
	v_rsq_f32_e32 v160, v160
	s_nop 0
	v_cndmask_b32_e64 v144, 0, v160, s[32:33]
	global_load_dwordx4 v[206:209], v172, s[64:65] offset:64
	global_load_dwordx4 v[210:213], v172, s[64:65] offset:80
	global_load_dwordx4 v[214:217], v172, s[64:65] offset:96
	global_load_dwordx4 v[218:221], v172, s[64:65] offset:112
	s_waitcnt vmcnt(4)
	v_pk_mul_f32 v[124:125], v[124:125], v[178:179] op_sel_hi:[1,0]
	v_pk_mul_f32 v[120:121], v[120:121], v[180:181] op_sel_hi:[1,0]
	v_pk_mul_f32 v[116:117], v[116:117], v[182:183] op_sel_hi:[1,0]
	v_pk_mul_f32 v[112:113], v[112:113], v[144:145] op_sel_hi:[1,0]
	v_pk_mul_f32 v[108:109], v[108:109], v[178:179] op_sel_hi:[1,0]
	v_pk_mul_f32 v[104:105], v[104:105], v[180:181] op_sel_hi:[1,0]
	v_pk_mul_f32 v[100:101], v[100:101], v[182:183] op_sel_hi:[1,0]
	v_pk_mul_f32 v[96:97], v[96:97], v[144:145] op_sel_hi:[1,0]
	s_nop 1
	v_mov_b32_dpp v248, v112 row_shr:1 row_mask:0xf bank_mask:0xf bound_ctrl:1
	v_mov_b32_dpp v249, v113 row_shr:1 row_mask:0xf bank_mask:0xf bound_ctrl:1
	v_mov_b32_dpp v250, v124 row_shl:1 row_mask:0xf bank_mask:0xf bound_ctrl:1
	v_mov_b32_dpp v251, v125 row_shl:1 row_mask:0xf bank_mask:0xf bound_ctrl:1
	v_pk_fma_f32 v[224:225], v[190:191], v[248:249], v[196:197]
	v_pk_fma_f32 v[226:227], v[190:191], v[124:125], v[196:197]
	v_pk_fma_f32 v[228:229], v[190:191], v[120:121], v[196:197]
	v_pk_fma_f32 v[230:231], v[190:191], v[116:117], v[196:197]
	v_pk_fma_f32 v[224:225], v[192:193], v[124:125], v[224:225]
	v_pk_fma_f32 v[226:227], v[192:193], v[120:121], v[226:227]
	v_pk_fma_f32 v[228:229], v[192:193], v[116:117], v[228:229]
	v_pk_fma_f32 v[230:231], v[192:193], v[112:113], v[230:231]
	v_pk_fma_f32 v[224:225], v[194:195], v[120:121], v[224:225]
	v_pk_fma_f32 v[226:227], v[194:195], v[116:117], v[226:227]
	v_pk_fma_f32 v[228:229], v[194:195], v[112:113], v[228:229]
	v_pk_fma_f32 v[230:231], v[194:195], v[250:251], v[230:231]
	s_nop 1
	v_mov_b32_dpp v248, v96 row_shr:1 row_mask:0xf bank_mask:0xf bound_ctrl:1
	v_mov_b32_dpp v249, v97 row_shr:1 row_mask:0xf bank_mask:0xf bound_ctrl:1
	v_mov_b32_dpp v250, v108 row_shl:1 row_mask:0xf bank_mask:0xf bound_ctrl:1
	v_mov_b32_dpp v251, v109 row_shl:1 row_mask:0xf bank_mask:0xf bound_ctrl:1
	v_pk_fma_f32 v[232:233], v[198:199], v[248:249], v[204:205]
	v_pk_fma_f32 v[234:235], v[198:199], v[108:109], v[204:205]
	v_pk_fma_f32 v[236:237], v[198:199], v[104:105], v[204:205]
	v_pk_fma_f32 v[238:239], v[198:199], v[100:101], v[204:205]
	v_pk_fma_f32 v[232:233], v[200:201], v[108:109], v[232:233]
	v_pk_fma_f32 v[234:235], v[200:201], v[104:105], v[234:235]
	v_pk_fma_f32 v[236:237], v[200:201], v[100:101], v[236:237]
	v_pk_fma_f32 v[238:239], v[200:201], v[96:97], v[238:239]
	v_pk_fma_f32 v[232:233], v[202:203], v[104:105], v[232:233]
	v_pk_fma_f32 v[234:235], v[202:203], v[100:101], v[234:235]
	v_pk_fma_f32 v[236:237], v[202:203], v[96:97], v[236:237]
	v_pk_fma_f32 v[238:239], v[202:203], v[250:251], v[238:239]
	v_exp_f32_e64 v240, -v232
	v_exp_f32_e64 v241, -v233
	v_exp_f32_e64 v242, -v234
	v_exp_f32_e64 v243, -v235
	v_exp_f32_e64 v244, -v236
	v_exp_f32_e64 v245, -v237
	v_exp_f32_e64 v246, -v238
	v_exp_f32_e64 v247, -v239
	v_pk_mul_f32 v[224:225], v[224:225], v[232:233]
	v_pk_mul_f32 v[226:227], v[226:227], v[234:235]
	v_pk_mul_f32 v[228:229], v[228:229], v[236:237]
	v_pk_mul_f32 v[230:231], v[230:231], v[238:239]
	v_pk_add_f32 v[240:241], v[240:241], 1.0 op_sel_hi:[1,0]
	v_pk_add_f32 v[242:243], v[242:243], 1.0 op_sel_hi:[1,0]
	v_pk_add_f32 v[244:245], v[244:245], 1.0 op_sel_hi:[1,0]
	v_pk_add_f32 v[246:247], v[246:247], 1.0 op_sel_hi:[1,0]
	v_rcp_f32_e32 v240, v240
	v_rcp_f32_e32 v241, v241
	v_rcp_f32_e32 v242, v242
	v_rcp_f32_e32 v243, v243
	v_rcp_f32_e32 v244, v244
	v_rcp_f32_e32 v245, v245
	v_rcp_f32_e32 v246, v246
	v_rcp_f32_e32 v247, v247
	s_nop 0
	v_pk_mul_f32 v[224:225], v[224:225], v[240:241]
	v_pk_mul_f32 v[226:227], v[226:227], v[242:243]
	v_pk_mul_f32 v[228:229], v[228:229], v[244:245]
	v_pk_mul_f32 v[230:231], v[230:231], v[246:247]
	v_cvt_pk_bf16_f32 v128, v224, v225
	v_cvt_pk_bf16_f32 v132, v226, v227
	v_cvt_pk_bf16_f32 v136, v228, v229
	v_cvt_pk_bf16_f32 v140, v230, v231
	global_load_dwordx4 v[190:193], v172, s[64:65] offset:128
	global_load_dwordx4 v[194:197], v172, s[64:65] offset:144
	global_load_dwordx4 v[198:201], v172, s[64:65] offset:160
	global_load_dwordx4 v[202:205], v172, s[64:65] offset:176
	s_waitcnt vmcnt(4)
;     __device__ __forceinline__ void operator()(const f32x4 (&acc)[2][2][4][2], const Unit& u, int wr, int wc, int fr, int fq) const {
;     ...
;                     const int cidx = (4 * n + 2 * jp) * 2;
;                     const f32x4 c0a = ct[cidx], c0b = ct[cidx + 1], c1a = ct[cidx + 2], c1b = ct[cidx + 3];
;                     const f32x2 wv0 = {c0a[0], c1a[0]}, wv1 = {c0a[1], c1a[1]}, wv2 = {c0a[2], c1a[2]}, bv = {c0a[3], c1a[3]};
;                     const f32x2 wg0 = {c0b[0], c1b[0]}, wg1 = {c0b[1], c1b[1]}, wg2 = {c0b[2], c1b[2]}, bg = {c0b[3], c1b[3]};
;                     f32x2 uv[4], ug[4], cv[4];
; #pragma unroll
;                     for (int m = 0; m < 4; ++m) { uv[m] = (f32x2){acc[ai][0][m][n][2 * jp], acc[ai][0][m][n][2 * jp + 1]}; ug[m] = (f32x2){acc[ai][1][m][n][2 * jp], acc[ai][1][m][n][2 * jp + 1]}; }
;                     asm volatile("" : "+v"(uv[0]), "+v"(uv[1]), "+v"(uv[2]), "+v"(uv[3]), "+v"(ug[0]), "+v"(ug[1]), "+v"(ug[2]), "+v"(ug[3]));
;                     {
;                         f32x2 rv[4], lv[4];
; #pragma unroll
;                         for (int m = 0; m < 4; ++m) { uv[m] = uv[m] * rs[m]; rv[m] = (f32x2){dpp_ror1(uv[m][0]), dpp_ror1(uv[m][1])}; lv[m] = (f32x2){dpp_ror15(uv[m][0]), dpp_ror15(uv[m][1])}; }
; #pragma unroll
;                         for (int m = 0; m < 4; ++m) { const f32x2 pv_ = (m > 0 && f0) ? rv[m > 0 ? m - 1 : 0] : rv[m], nv_ = (m < 3 && f15) ? lv[m < 3 ? m + 1 : 3] : lv[m];
;                             cv[m] = bv + wv0 * pv_ + wv1 * uv[m] + wv2 * nv_; }
;                     }
;                     asm volatile("" : "+v"(cv[0]), "+v"(cv[1]), "+v"(cv[2]), "+v"(cv[3]));
;                     {
;                         f32x2 rg[4], lg[4];
; #pragma unroll
;                         for (int m = 0; m < 4; ++m) { ug[m] = ug[m] * rs[m]; rg[m] = (f32x2){dpp_ror1(ug[m][0]), dpp_ror1(ug[m][1])}; lg[m] = (f32x2){dpp_ror15(ug[m][0]), dpp_ror15(ug[m][1])}; }
; #pragma unroll
;                         for (int m = 0; m < 4; ++m) { const f32x2 pg_ = (m > 0 && f0) ? rg[m > 0 ? m - 1 : 0] : rg[m], ng_ = (m < 3 && f15) ? lg[m < 3 ? m + 1 : 3] : lg[m];
;                             const f32x2 cgt = bg + wg0 * pg_ + wg1 * ug[m] + wg2 * ng_;
;                             const f32x2 e = cgt * (-LOG2E);
;                             const f32x2 d = (f32x2){__builtin_amdgcn_exp2f(e[0]), __builtin_amdgcn_exp2f(e[1])} + 1.f;
	v_pk_mul_f32 v[126:127], v[126:127], v[178:179] op_sel_hi:[1,0]
	v_pk_mul_f32 v[122:123], v[122:123], v[180:181] op_sel_hi:[1,0]
	v_pk_mul_f32 v[118:119], v[118:119], v[182:183] op_sel_hi:[1,0]
	v_pk_mul_f32 v[114:115], v[114:115], v[144:145] op_sel_hi:[1,0]
	v_pk_mul_f32 v[110:111], v[110:111], v[178:179] op_sel_hi:[1,0]
	v_pk_mul_f32 v[106:107], v[106:107], v[180:181] op_sel_hi:[1,0]
	v_pk_mul_f32 v[102:103], v[102:103], v[182:183] op_sel_hi:[1,0]
	v_pk_mul_f32 v[98:99], v[98:99], v[144:145] op_sel_hi:[1,0]
	s_nop 1
	v_mov_b32_dpp v248, v114 row_shr:1 row_mask:0xf bank_mask:0xf bound_ctrl:1
	v_mov_b32_dpp v249, v115 row_shr:1 row_mask:0xf bank_mask:0xf bound_ctrl:1
	v_mov_b32_dpp v250, v126 row_shl:1 row_mask:0xf bank_mask:0xf bound_ctrl:1
	v_mov_b32_dpp v251, v127 row_shl:1 row_mask:0xf bank_mask:0xf bound_ctrl:1
	v_pk_fma_f32 v[224:225], v[206:207], v[248:249], v[212:213]
	v_pk_fma_f32 v[226:227], v[206:207], v[126:127], v[212:213]
	v_pk_fma_f32 v[228:229], v[206:207], v[122:123], v[212:213]
	v_pk_fma_f32 v[230:231], v[206:207], v[118:119], v[212:213]
	v_pk_fma_f32 v[224:225], v[208:209], v[126:127], v[224:225]
	v_pk_fma_f32 v[226:227], v[208:209], v[122:123], v[226:227]
	v_pk_fma_f32 v[228:229], v[208:209], v[118:119], v[228:229]
	v_pk_fma_f32 v[230:231], v[208:209], v[114:115], v[230:231]
	v_pk_fma_f32 v[224:225], v[210:211], v[122:123], v[224:225]
	v_pk_fma_f32 v[226:227], v[210:211], v[118:119], v[226:227]
	v_pk_fma_f32 v[228:229], v[210:211], v[114:115], v[228:229]
	v_pk_fma_f32 v[230:231], v[210:211], v[250:251], v[230:231]
	s_nop 1
	v_mov_b32_dpp v248, v98 row_shr:1 row_mask:0xf bank_mask:0xf bound_ctrl:1
	v_mov_b32_dpp v249, v99 row_shr:1 row_mask:0xf bank_mask:0xf bound_ctrl:1
	v_mov_b32_dpp v250, v110 row_shl:1 row_mask:0xf bank_mask:0xf bound_ctrl:1
	v_mov_b32_dpp v251, v111 row_shl:1 row_mask:0xf bank_mask:0xf bound_ctrl:1
	v_pk_fma_f32 v[232:233], v[214:215], v[248:249], v[220:221]
	v_pk_fma_f32 v[234:235], v[214:215], v[110:111], v[220:221]
	v_pk_fma_f32 v[236:237], v[214:215], v[106:107], v[220:221]
	v_pk_fma_f32 v[238:239], v[214:215], v[102:103], v[220:221]
	v_pk_fma_f32 v[232:233], v[216:217], v[110:111], v[232:233]
	v_pk_fma_f32 v[234:235], v[216:217], v[106:107], v[234:235]
	v_pk_fma_f32 v[236:237], v[216:217], v[102:103], v[236:237]
	v_pk_fma_f32 v[238:239], v[216:217], v[98:99], v[238:239]
	v_pk_fma_f32 v[232:233], v[218:219], v[106:107], v[232:233]
	v_pk_fma_f32 v[234:235], v[218:219], v[102:103], v[234:235]
	v_pk_fma_f32 v[236:237], v[218:219], v[98:99], v[236:237]
	v_pk_fma_f32 v[238:239], v[218:219], v[250:251], v[238:239]
	v_exp_f32_e64 v240, -v232
	v_exp_f32_e64 v241, -v233
	v_exp_f32_e64 v242, -v234
	v_exp_f32_e64 v243, -v235
	v_exp_f32_e64 v244, -v236
	v_exp_f32_e64 v245, -v237
	v_exp_f32_e64 v246, -v238
	v_exp_f32_e64 v247, -v239
	v_pk_mul_f32 v[224:225], v[224:225], v[232:233]
	v_pk_mul_f32 v[226:227], v[226:227], v[234:235]
	v_pk_mul_f32 v[228:229], v[228:229], v[236:237]
	v_pk_mul_f32 v[230:231], v[230:231], v[238:239]
	v_pk_add_f32 v[240:241], v[240:241], 1.0 op_sel_hi:[1,0]
	v_pk_add_f32 v[242:243], v[242:243], 1.0 op_sel_hi:[1,0]
	v_pk_add_f32 v[244:245], v[244:245], 1.0 op_sel_hi:[1,0]
	v_pk_add_f32 v[246:247], v[246:247], 1.0 op_sel_hi:[1,0]
	v_rcp_f32_e32 v240, v240
	v_rcp_f32_e32 v241, v241
	v_rcp_f32_e32 v242, v242
	v_rcp_f32_e32 v243, v243
	v_rcp_f32_e32 v244, v244
	v_rcp_f32_e32 v245, v245
	v_rcp_f32_e32 v246, v246
	v_rcp_f32_e32 v247, v247
	s_nop 0
	v_pk_mul_f32 v[224:225], v[224:225], v[240:241]
	v_pk_mul_f32 v[226:227], v[226:227], v[242:243]
	v_pk_mul_f32 v[228:229], v[228:229], v[244:245]
	v_pk_mul_f32 v[230:231], v[230:231], v[246:247]
	v_cvt_pk_bf16_f32 v129, v224, v225
	v_cvt_pk_bf16_f32 v133, v226, v227
	v_cvt_pk_bf16_f32 v137, v228, v229
	v_cvt_pk_bf16_f32 v141, v230, v231
	global_load_dwordx4 v[206:209], v172, s[64:65] offset:192
	global_load_dwordx4 v[210:213], v172, s[64:65] offset:208
	global_load_dwordx4 v[214:217], v172, s[64:65] offset:224
	global_load_dwordx4 v[218:221], v172, s[64:65] offset:240
	s_waitcnt vmcnt(4)
	v_pk_mul_f32 v[92:93], v[92:93], v[178:179] op_sel_hi:[1,0]
	v_pk_mul_f32 v[88:89], v[88:89], v[180:181] op_sel_hi:[1,0]
	v_pk_mul_f32 v[84:85], v[84:85], v[182:183] op_sel_hi:[1,0]
	v_pk_mul_f32 v[80:81], v[80:81], v[144:145] op_sel_hi:[1,0]
	v_pk_mul_f32 v[76:77], v[76:77], v[178:179] op_sel_hi:[1,0]
	v_pk_mul_f32 v[72:73], v[72:73], v[180:181] op_sel_hi:[1,0]
	v_pk_mul_f32 v[68:69], v[68:69], v[182:183] op_sel_hi:[1,0]
	v_pk_mul_f32 v[64:65], v[64:65], v[144:145] op_sel_hi:[1,0]
	s_nop 1
	v_mov_b32_dpp v248, v80 row_shr:1 row_mask:0xf bank_mask:0xf bound_ctrl:1
	v_mov_b32_dpp v249, v81 row_shr:1 row_mask:0xf bank_mask:0xf bound_ctrl:1
	v_mov_b32_dpp v250, v92 row_shl:1 row_mask:0xf bank_mask:0xf bound_ctrl:1
	v_mov_b32_dpp v251, v93 row_shl:1 row_mask:0xf bank_mask:0xf bound_ctrl:1
	v_pk_fma_f32 v[224:225], v[190:191], v[248:249], v[196:197]
	v_pk_fma_f32 v[226:227], v[190:191], v[92:93], v[196:197]
	v_pk_fma_f32 v[228:229], v[190:191], v[88:89], v[196:197]
	v_pk_fma_f32 v[230:231], v[190:191], v[84:85], v[196:197]
	v_pk_fma_f32 v[224:225], v[192:193], v[92:93], v[224:225]
	v_pk_fma_f32 v[226:227], v[192:193], v[88:89], v[226:227]
	v_pk_fma_f32 v[228:229], v[192:193], v[84:85], v[228:229]
	v_pk_fma_f32 v[230:231], v[192:193], v[80:81], v[230:231]
	v_pk_fma_f32 v[224:225], v[194:195], v[88:89], v[224:225]
	v_pk_fma_f32 v[226:227], v[194:195], v[84:85], v[226:227]
	v_pk_fma_f32 v[228:229], v[194:195], v[80:81], v[228:229]
	v_pk_fma_f32 v[230:231], v[194:195], v[250:251], v[230:231]
	s_nop 1
	v_mov_b32_dpp v248, v64 row_shr:1 row_mask:0xf bank_mask:0xf bound_ctrl:1
;     __device__ __forceinline__ void operator()(const f32x4 (&acc)[2][2][4][2], const Unit& u, int wr, int wc, int fr, int fq) const {
;     ...
;                     const int cidx = (4 * n + 2 * jp) * 2;
;                     const f32x4 c0a = ct[cidx], c0b = ct[cidx + 1], c1a = ct[cidx + 2], c1b = ct[cidx + 3];
;                     const f32x2 wv0 = {c0a[0], c1a[0]}, wv1 = {c0a[1], c1a[1]}, wv2 = {c0a[2], c1a[2]}, bv = {c0a[3], c1a[3]};
;                     const f32x2 wg0 = {c0b[0], c1b[0]}, wg1 = {c0b[1], c1b[1]}, wg2 = {c0b[2], c1b[2]}, bg = {c0b[3], c1b[3]};
;                     f32x2 uv[4], ug[4], cv[4];
; #pragma unroll
;                     for (int m = 0; m < 4; ++m) { uv[m] = (f32x2){acc[ai][0][m][n][2 * jp], acc[ai][0][m][n][2 * jp + 1]}; ug[m] = (f32x2){acc[ai][1][m][n][2 * jp], acc[ai][1][m][n][2 * jp + 1]}; }
;                     asm volatile("" : "+v"(uv[0]), "+v"(uv[1]), "+v"(uv[2]), "+v"(uv[3]), "+v"(ug[0]), "+v"(ug[1]), "+v"(ug[2]), "+v"(ug[3]));
;                     {
;                         f32x2 rv[4], lv[4];
; #pragma unroll
;                         for (int m = 0; m < 4; ++m) { uv[m] = uv[m] * rs[m]; rv[m] = (f32x2){dpp_ror1(uv[m][0]), dpp_ror1(uv[m][1])}; lv[m] = (f32x2){dpp_ror15(uv[m][0]), dpp_ror15(uv[m][1])}; }
; #pragma unroll
;                         for (int m = 0; m < 4; ++m) { const f32x2 pv_ = (m > 0 && f0) ? rv[m > 0 ? m - 1 : 0] : rv[m], nv_ = (m < 3 && f15) ? lv[m < 3 ? m + 1 : 3] : lv[m];
;                             cv[m] = bv + wv0 * pv_ + wv1 * uv[m] + wv2 * nv_; }
;                     }
;                     asm volatile("" : "+v"(cv[0]), "+v"(cv[1]), "+v"(cv[2]), "+v"(cv[3]));
;                     {
;                         f32x2 rg[4], lg[4];
; #pragma unroll
;                         for (int m = 0; m < 4; ++m) { ug[m] = ug[m] * rs[m]; rg[m] = (f32x2){dpp_ror1(ug[m][0]), dpp_ror1(ug[m][1])}; lg[m] = (f32x2){dpp_ror15(ug[m][0]), dpp_ror15(ug[m][1])}; }
; #pragma unroll
;                         for (int m = 0; m < 4; ++m) { const f32x2 pg_ = (m > 0 && f0) ? rg[m > 0 ? m - 1 : 0] : rg[m], ng_ = (m < 3 && f15) ? lg[m < 3 ? m + 1 : 3] : lg[m];
;                             const f32x2 cgt = bg + wg0 * pg_ + wg1 * ug[m] + wg2 * ng_;
;                             const f32x2 e = cgt * (-LOG2E);
;                             const f32x2 d = (f32x2){__builtin_amdgcn_exp2f(e[0]), __builtin_amdgcn_exp2f(e[1])} + 1.f;
	v_mov_b32_dpp v249, v65 row_shr:1 row_mask:0xf bank_mask:0xf bound_ctrl:1
	v_mov_b32_dpp v250, v76 row_shl:1 row_mask:0xf bank_mask:0xf bound_ctrl:1
	v_mov_b32_dpp v251, v77 row_shl:1 row_mask:0xf bank_mask:0xf bound_ctrl:1
	v_pk_fma_f32 v[232:233], v[198:199], v[248:249], v[204:205]
	v_pk_fma_f32 v[234:235], v[198:199], v[76:77], v[204:205]
	v_pk_fma_f32 v[236:237], v[198:199], v[72:73], v[204:205]
	v_pk_fma_f32 v[238:239], v[198:199], v[68:69], v[204:205]
	v_pk_fma_f32 v[232:233], v[200:201], v[76:77], v[232:233]
	v_pk_fma_f32 v[234:235], v[200:201], v[72:73], v[234:235]
	v_pk_fma_f32 v[236:237], v[200:201], v[68:69], v[236:237]
	v_pk_fma_f32 v[238:239], v[200:201], v[64:65], v[238:239]
	v_pk_fma_f32 v[232:233], v[202:203], v[72:73], v[232:233]
	v_pk_fma_f32 v[234:235], v[202:203], v[68:69], v[234:235]
	v_pk_fma_f32 v[236:237], v[202:203], v[64:65], v[236:237]
	v_pk_fma_f32 v[238:239], v[202:203], v[250:251], v[238:239]
	v_exp_f32_e64 v240, -v232
	v_exp_f32_e64 v241, -v233
	v_exp_f32_e64 v242, -v234
	v_exp_f32_e64 v243, -v235
	v_exp_f32_e64 v244, -v236
	v_exp_f32_e64 v245, -v237
	v_exp_f32_e64 v246, -v238
	v_exp_f32_e64 v247, -v239
	v_pk_mul_f32 v[224:225], v[224:225], v[232:233]
	v_pk_mul_f32 v[226:227], v[226:227], v[234:235]
	v_pk_mul_f32 v[228:229], v[228:229], v[236:237]
	v_pk_mul_f32 v[230:231], v[230:231], v[238:239]
	v_pk_add_f32 v[240:241], v[240:241], 1.0 op_sel_hi:[1,0]
	v_pk_add_f32 v[242:243], v[242:243], 1.0 op_sel_hi:[1,0]
	v_pk_add_f32 v[244:245], v[244:245], 1.0 op_sel_hi:[1,0]
	v_pk_add_f32 v[246:247], v[246:247], 1.0 op_sel_hi:[1,0]
	v_rcp_f32_e32 v240, v240
	v_rcp_f32_e32 v241, v241
	v_rcp_f32_e32 v242, v242
	v_rcp_f32_e32 v243, v243
	v_rcp_f32_e32 v244, v244
	v_rcp_f32_e32 v245, v245
	v_rcp_f32_e32 v246, v246
	v_rcp_f32_e32 v247, v247
	s_nop 0
	v_pk_mul_f32 v[224:225], v[224:225], v[240:241]
	v_pk_mul_f32 v[226:227], v[226:227], v[242:243]
	v_pk_mul_f32 v[228:229], v[228:229], v[244:245]
	v_pk_mul_f32 v[230:231], v[230:231], v[246:247]
	v_cvt_pk_bf16_f32 v130, v224, v225
	v_cvt_pk_bf16_f32 v134, v226, v227
	v_cvt_pk_bf16_f32 v138, v228, v229
	v_cvt_pk_bf16_f32 v142, v230, v231
	s_waitcnt vmcnt(0)
	v_add_u32_e32 v253, 0x7c, v174
	v_add_u32_e32 v176, 0, v253
	v_cmp_gt_u32_e64 s[52:53], s91, v176
	s_nop 1
	v_cndmask_b32_e64 v176, 0, v176, s[52:53]
	v_add_u32_e32 v176, s88, v176
	v_lshl_add_u32 v248, v176, 6, v165
	global_load_dwordx4 v[190:193], v248, s[70:71]
	v_add_u32_e32 v176, 1, v253
	v_cmp_gt_u32_e64 s[2:3], s91, v176
	s_nop 1
	v_cndmask_b32_e64 v176, 0, v176, s[2:3]
	v_add_u32_e32 v176, s88, v176
	v_lshl_add_u32 v249, v176, 6, v165
	global_load_dwordx4 v[194:197], v249, s[70:71]
	v_add_u32_e32 v176, 2, v253
	v_cmp_gt_u32_e64 s[18:19], s91, v176
	s_nop 1
	v_cndmask_b32_e64 v176, 0, v176, s[18:19]
	v_add_u32_e32 v176, s88, v176
	v_lshl_add_u32 v250, v176, 6, v165
	global_load_dwordx4 v[198:201], v250, s[70:71]
	v_add_u32_e32 v176, 3, v253
	v_cmp_gt_u32_e64 s[32:33], s91, v176
	s_nop 1
	v_cndmask_b32_e64 v176, 0, v176, s[32:33]
	v_add_u32_e32 v176, s88, v176
	v_lshl_add_u32 v251, v176, 6, v165
	global_load_dwordx4 v[202:205], v251, s[70:71]
	v_pk_mul_f32 v[94:95], v[94:95], v[178:179] op_sel_hi:[1,0]
	v_pk_mul_f32 v[90:91], v[90:91], v[180:181] op_sel_hi:[1,0]
	v_pk_mul_f32 v[86:87], v[86:87], v[182:183] op_sel_hi:[1,0]
	v_pk_mul_f32 v[82:83], v[82:83], v[144:145] op_sel_hi:[1,0]
	v_pk_mul_f32 v[78:79], v[78:79], v[178:179] op_sel_hi:[1,0]
	v_pk_mul_f32 v[74:75], v[74:75], v[180:181] op_sel_hi:[1,0]
	v_pk_mul_f32 v[70:71], v[70:71], v[182:183] op_sel_hi:[1,0]
	v_pk_mul_f32 v[66:67], v[66:67], v[144:145] op_sel_hi:[1,0]
	s_nop 1
	v_mov_b32_dpp v248, v82 row_shr:1 row_mask:0xf bank_mask:0xf bound_ctrl:1
	v_mov_b32_dpp v249, v83 row_shr:1 row_mask:0xf bank_mask:0xf bound_ctrl:1
	v_mov_b32_dpp v250, v94 row_shl:1 row_mask:0xf bank_mask:0xf bound_ctrl:1
	v_mov_b32_dpp v251, v95 row_shl:1 row_mask:0xf bank_mask:0xf bound_ctrl:1
	v_pk_fma_f32 v[224:225], v[206:207], v[248:249], v[212:213]
	v_pk_fma_f32 v[226:227], v[206:207], v[94:95], v[212:213]
	v_pk_fma_f32 v[228:229], v[206:207], v[90:91], v[212:213]
	v_pk_fma_f32 v[230:231], v[206:207], v[86:87], v[212:213]
	v_pk_fma_f32 v[224:225], v[208:209], v[94:95], v[224:225]
	v_pk_fma_f32 v[226:227], v[208:209], v[90:91], v[226:227]
	v_pk_fma_f32 v[228:229], v[208:209], v[86:87], v[228:229]
	v_pk_fma_f32 v[230:231], v[208:209], v[82:83], v[230:231]
	v_pk_fma_f32 v[224:225], v[210:211], v[90:91], v[224:225]
	v_pk_fma_f32 v[226:227], v[210:211], v[86:87], v[226:227]
	v_pk_fma_f32 v[228:229], v[210:211], v[82:83], v[228:229]
	v_pk_fma_f32 v[230:231], v[210:211], v[250:251], v[230:231]
	s_nop 1
	v_mov_b32_dpp v248, v66 row_shr:1 row_mask:0xf bank_mask:0xf bound_ctrl:1
	v_mov_b32_dpp v249, v67 row_shr:1 row_mask:0xf bank_mask:0xf bound_ctrl:1
	v_mov_b32_dpp v250, v78 row_shl:1 row_mask:0xf bank_mask:0xf bound_ctrl:1
	v_mov_b32_dpp v251, v79 row_shl:1 row_mask:0xf bank_mask:0xf bound_ctrl:1
	v_pk_fma_f32 v[232:233], v[214:215], v[248:249], v[220:221]
	v_pk_fma_f32 v[234:235], v[214:215], v[78:79], v[220:221]
	v_pk_fma_f32 v[236:237], v[214:215], v[74:75], v[220:221]
	v_pk_fma_f32 v[238:239], v[214:215], v[70:71], v[220:221]
	v_pk_fma_f32 v[232:233], v[216:217], v[78:79], v[232:233]
	v_pk_fma_f32 v[234:235], v[216:217], v[74:75], v[234:235]
	v_pk_fma_f32 v[236:237], v[216:217], v[70:71], v[236:237]
	v_pk_fma_f32 v[238:239], v[216:217], v[66:67], v[238:239]
	v_pk_fma_f32 v[232:233], v[218:219], v[74:75], v[232:233]
	v_pk_fma_f32 v[234:235], v[218:219], v[70:71], v[234:235]
	v_pk_fma_f32 v[236:237], v[218:219], v[66:67], v[236:237]
	v_pk_fma_f32 v[238:239], v[218:219], v[250:251], v[238:239]
; __device__ __forceinline__ unsigned cvtpk(float lo, float hi) { f32x2 v = {lo, hi}; bf16x2_t b = __builtin_convertvector(v, bf16x2_t); return __builtin_bit_cast(unsigned, b); }
; __device__ __forceinline__ float dpp_ror1(float x) { return __builtin_bit_cast(float, __builtin_amdgcn_mov_dpp(__builtin_bit_cast(int, x), 0x121, 0xF, 0xF, true)); }
;     __device__ __forceinline__ void operator()(const f32x4 (&acc)[2][2][4][2], const Unit& u, int wr, int wc, int fr, int fq) const {
;     ...
;             for (int m = 0; m < 4; ++m) { const int t = tbase + 16 * m + fr; const bool vin = (t >= 0) && (t < slen); const int grow = seqbase + (vin ? t : 0);
;                 const f32x4 p = *(const f32x4*)(PS + (size_t)grow * 16 + 4 * fq); float s = (p[0] + p[1]) + (p[2] + p[3]); s = bfly_add<16>(s); s = bfly_add<32>(s); rs[m] = vin ? rsqrtf(s * (1.f / DM) + EPS) : 0.f; }
;     ...
;                         for (int m = 0; m < 4; ++m) { ug[m] = ug[m] * rs[m]; rg[m] = (f32x2){dpp_ror1(ug[m][0]), dpp_ror1(ug[m][1])}; lg[m] = (f32x2){dpp_ror15(ug[m][0]), dpp_ror15(ug[m][1])}; }
; #pragma unroll
;                         for (int m = 0; m < 4; ++m) { const f32x2 pg_ = (m > 0 && f0) ? rg[m > 0 ? m - 1 : 0] : rg[m], ng_ = (m < 3 && f15) ? lg[m < 3 ? m + 1 : 3] : lg[m];
;                             const f32x2 cgt = bg + wg0 * pg_ + wg1 * ug[m] + wg2 * ng_;
;                             const f32x2 e = cgt * (-LOG2E);
;                             const f32x2 d = (f32x2){__builtin_amdgcn_exp2f(e[0]), __builtin_amdgcn_exp2f(e[1])} + 1.f;
;                             const f32x2 sg = {__builtin_amdgcn_rcpf(d[0]), __builtin_amdgcn_rcpf(d[1])};
;                             const f32x2 ov = cv[m] * cgt * sg;
;                             outw[m][n][jp] = cvtpk(ov[0], ov[1]); }
;                     }
;                     asm volatile("" : "+v"(outw[0][n][jp]), "+v"(outw[1][n][jp]), "+v"(outw[2][n][jp]), "+v"(outw[3][n][jp]) :: "memory"); __builtin_amdgcn_sched_barrier(0);
;                 }
; #pragma unroll
;             for (int m = 0; m < 4; ++m) { const int i = 16 * m + fr, t = tbase + i;
;                 if (i >= 1 && i <= 62 && t < slen) { u32x4 w; w.x = outw[m][0][0]; w.y = outw[m][0][1]; w.z = outw[m][1][0]; w.w = outw[m][1][1];
;                     *(u32x4*)(Gout + (size_t)(seqbase + t) * DFF + 128 * u.pn + 32 * wc + 8 * fq) = w; } }
	v_exp_f32_e64 v240, -v232
	v_exp_f32_e64 v241, -v233
	v_exp_f32_e64 v242, -v234
	v_exp_f32_e64 v243, -v235
	v_exp_f32_e64 v244, -v236
	v_exp_f32_e64 v245, -v237
	v_exp_f32_e64 v246, -v238
	v_exp_f32_e64 v247, -v239
	v_pk_mul_f32 v[224:225], v[224:225], v[232:233]
	v_pk_mul_f32 v[226:227], v[226:227], v[234:235]
	v_pk_mul_f32 v[228:229], v[228:229], v[236:237]
	v_pk_mul_f32 v[230:231], v[230:231], v[238:239]
	v_pk_add_f32 v[240:241], v[240:241], 1.0 op_sel_hi:[1,0]
	v_pk_add_f32 v[242:243], v[242:243], 1.0 op_sel_hi:[1,0]
	v_pk_add_f32 v[244:245], v[244:245], 1.0 op_sel_hi:[1,0]
	v_pk_add_f32 v[246:247], v[246:247], 1.0 op_sel_hi:[1,0]
	v_rcp_f32_e32 v240, v240
	v_rcp_f32_e32 v241, v241
	v_rcp_f32_e32 v242, v242
	v_rcp_f32_e32 v243, v243
	v_rcp_f32_e32 v244, v244
	v_rcp_f32_e32 v245, v245
	v_rcp_f32_e32 v246, v246
	v_rcp_f32_e32 v247, v247
	s_nop 0
	v_pk_mul_f32 v[224:225], v[224:225], v[240:241]
	v_pk_mul_f32 v[226:227], v[226:227], v[242:243]
	v_pk_mul_f32 v[228:229], v[228:229], v[244:245]
	v_pk_mul_f32 v[230:231], v[230:231], v[246:247]
	v_cvt_pk_bf16_f32 v131, v224, v225
	v_cvt_pk_bf16_f32 v135, v226, v227
	v_cvt_pk_bf16_f32 v139, v228, v229
	v_cvt_pk_bf16_f32 v143, v230, v231
	s_sub_i32 s51, s91, s89
	s_sub_i32 s66, s51, 4
	s_max_i32 s66, s66, 0
	v_add_u32_e32 v176, -4, v164
	v_cmp_gt_u32_e32 vcc, s66, v176
	v_add_u32_e32 v176, 0, v174
	v_add_u32_e32 v176, s88, v176
	v_mad_u32_u24 v248, v176, s54, v165
	s_mov_b64 exec, vcc
	global_store_dwordx4 v248, v[128:131], s[86:87]
	s_mov_b64 exec, -1
	s_sub_i32 s66, s51, 1
	s_max_i32 s66, s66, 0
	v_cmp_gt_u32_e32 vcc, s66, v164
	v_add_u32_e32 v176, 1, v174
	v_add_u32_e32 v176, s88, v176
	v_mad_u32_u24 v249, v176, s54, v165
	s_mov_b64 exec, vcc
	global_store_dwordx4 v249, v[132:135], s[86:87]
	s_mov_b64 exec, -1
	s_sub_i32 s66, s51, 2
	s_max_i32 s66, s66, 0
	v_cmp_gt_u32_e32 vcc, s66, v164
	v_add_u32_e32 v176, 2, v174
	v_add_u32_e32 v176, s88, v176
	v_mad_u32_u24 v250, v176, s54, v165
	s_mov_b64 exec, vcc
	global_store_dwordx4 v250, v[136:139], s[86:87]
	s_mov_b64 exec, -1
	s_sub_i32 s66, s51, 3
	s_min_i32 s66, s66, 60
	s_max_i32 s66, s66, 0
	v_cmp_gt_u32_e32 vcc, s66, v164
	v_add_u32_e32 v176, 3, v174
	v_add_u32_e32 v176, s88, v176
	v_mad_u32_u24 v251, v176, s54, v165
	s_mov_b64 exec, vcc
	global_store_dwordx4 v251, v[140:143], s[86:87]
	s_mov_b64 exec, -1
	s_addk_i32 s89, 0x7c
	v_mov_b32_e32 v174, v253
	global_load_dwordx4 v[206:209], v172, s[64:65]
	global_load_dwordx4 v[210:213], v172, s[64:65] offset:16
	global_load_dwordx4 v[214:217], v172, s[64:65] offset:32
	global_load_dwordx4 v[218:221], v172, s[64:65] offset:48
	s_waitcnt vmcnt(11)
	v_add_f32_e32 v190, v190, v191
	v_add_f32_e32 v192, v192, v193
	v_add_f32_e32 v190, v190, v192
	v_mov_b32_e32 v191, v190
	s_nop 1
	v_permlane16_swap_b32_e32 v190, v191
	v_add_f32_e32 v190, v190, v191
	v_mov_b32_e32 v191, v190
	s_nop 1
	v_permlane32_swap_b32_e32 v190, v191
	v_add_f32_e32 v190, v190, v191
	v_fma_f32 v190, v190, s82, v252
	v_rsq_f32_e32 v190, v190
	s_nop 0
	v_cndmask_b32_e64 v178, 0, v190, s[52:53]
	s_waitcnt vmcnt(10)
	v_add_f32_e32 v194, v194, v195
	v_add_f32_e32 v196, v196, v197
	v_add_f32_e32 v194, v194, v196
	v_mov_b32_e32 v195, v194
	s_nop 1
	v_permlane16_swap_b32_e32 v194, v195
	v_add_f32_e32 v194, v194, v195
	v_mov_b32_e32 v195, v194
	s_nop 1
	v_permlane32_swap_b32_e32 v194, v195
	v_add_f32_e32 v194, v194, v195
	v_fma_f32 v194, v194, s82, v252
	v_rsq_f32_e32 v194, v194
	s_nop 0
	v_cndmask_b32_e64 v180, 0, v194, s[2:3]
	s_waitcnt vmcnt(9)
	v_add_f32_e32 v198, v198, v199
	v_add_f32_e32 v200, v200, v201
	v_add_f32_e32 v198, v198, v200
	v_mov_b32_e32 v199, v198
	s_nop 1
	v_permlane16_swap_b32_e32 v198, v199
	v_add_f32_e32 v198, v198, v199
	v_mov_b32_e32 v199, v198
	s_nop 1
	v_permlane32_swap_b32_e32 v198, v199
	v_add_f32_e32 v198, v198, v199
	v_fma_f32 v198, v198, s82, v252
	v_rsq_f32_e32 v198, v198
	s_nop 0
	v_cndmask_b32_e64 v182, 0, v198, s[18:19]
	s_waitcnt vmcnt(8)
	v_add_f32_e32 v202, v202, v203
	v_add_f32_e32 v204, v204, v205
	v_add_f32_e32 v202, v202, v204
	v_mov_b32_e32 v203, v202
	s_nop 1
	v_permlane16_swap_b32_e32 v202, v203
	v_add_f32_e32 v202, v202, v203
	v_mov_b32_e32 v203, v202
	s_nop 1
	v_permlane32_swap_b32_e32 v202, v203
	v_add_f32_e32 v202, v202, v203
	v_fma_f32 v202, v202, s82, v252
	v_rsq_f32_e32 v202, v202
	s_nop 0
	v_cndmask_b32_e64 v144, 0, v202, s[32:33]
	global_load_dwordx4 v[190:193], v172, s[64:65] offset:64
	global_load_dwordx4 v[194:197], v172, s[64:65] offset:80
	global_load_dwordx4 v[198:201], v172, s[64:65] offset:96
	global_load_dwordx4 v[202:205], v172, s[64:65] offset:112
	s_waitcnt vmcnt(4)
;     __device__ __forceinline__ void operator()(const f32x4 (&acc)[2][2][4][2], const Unit& u, int wr, int wc, int fr, int fq) const {
;     ...
;                     const int cidx = (4 * n + 2 * jp) * 2;
;                     const f32x4 c0a = ct[cidx], c0b = ct[cidx + 1], c1a = ct[cidx + 2], c1b = ct[cidx + 3];
;                     const f32x2 wv0 = {c0a[0], c1a[0]}, wv1 = {c0a[1], c1a[1]}, wv2 = {c0a[2], c1a[2]}, bv = {c0a[3], c1a[3]};
;                     const f32x2 wg0 = {c0b[0], c1b[0]}, wg1 = {c0b[1], c1b[1]}, wg2 = {c0b[2], c1b[2]}, bg = {c0b[3], c1b[3]};
;                     f32x2 uv[4], ug[4], cv[4];
; #pragma unroll
;                     for (int m = 0; m < 4; ++m) { uv[m] = (f32x2){acc[ai][0][m][n][2 * jp], acc[ai][0][m][n][2 * jp + 1]}; ug[m] = (f32x2){acc[ai][1][m][n][2 * jp], acc[ai][1][m][n][2 * jp + 1]}; }
;                     asm volatile("" : "+v"(uv[0]), "+v"(uv[1]), "+v"(uv[2]), "+v"(uv[3]), "+v"(ug[0]), "+v"(ug[1]), "+v"(ug[2]), "+v"(ug[3]));
;                     {
;                         f32x2 rv[4], lv[4];
; #pragma unroll
;                         for (int m = 0; m < 4; ++m) { uv[m] = uv[m] * rs[m]; rv[m] = (f32x2){dpp_ror1(uv[m][0]), dpp_ror1(uv[m][1])}; lv[m] = (f32x2){dpp_ror15(uv[m][0]), dpp_ror15(uv[m][1])}; }
; #pragma unroll
;                         for (int m = 0; m < 4; ++m) { const f32x2 pv_ = (m > 0 && f0) ? rv[m > 0 ? m - 1 : 0] : rv[m], nv_ = (m < 3 && f15) ? lv[m < 3 ? m + 1 : 3] : lv[m];
;                             cv[m] = bv + wv0 * pv_ + wv1 * uv[m] + wv2 * nv_; }
;                     }
;                     asm volatile("" : "+v"(cv[0]), "+v"(cv[1]), "+v"(cv[2]), "+v"(cv[3]));
;                     {
;                         f32x2 rg[4], lg[4];
; #pragma unroll
;                         for (int m = 0; m < 4; ++m) { ug[m] = ug[m] * rs[m]; rg[m] = (f32x2){dpp_ror1(ug[m][0]), dpp_ror1(ug[m][1])}; lg[m] = (f32x2){dpp_ror15(ug[m][0]), dpp_ror15(ug[m][1])}; }
; #pragma unroll
;                         for (int m = 0; m < 4; ++m) { const f32x2 pg_ = (m > 0 && f0) ? rg[m > 0 ? m - 1 : 0] : rg[m], ng_ = (m < 3 && f15) ? lg[m < 3 ? m + 1 : 3] : lg[m];
;                             const f32x2 cgt = bg + wg0 * pg_ + wg1 * ug[m] + wg2 * ng_;
;                             const f32x2 e = cgt * (-LOG2E);
;                             const f32x2 d = (f32x2){__builtin_amdgcn_exp2f(e[0]), __builtin_amdgcn_exp2f(e[1])} + 1.f;
	v_pk_mul_f32 v[60:61], v[60:61], v[178:179] op_sel_hi:[1,0]
	v_pk_mul_f32 v[56:57], v[56:57], v[180:181] op_sel_hi:[1,0]
	v_pk_mul_f32 v[52:53], v[52:53], v[182:183] op_sel_hi:[1,0]
	v_pk_mul_f32 v[48:49], v[48:49], v[144:145] op_sel_hi:[1,0]
	v_pk_mul_f32 v[44:45], v[44:45], v[178:179] op_sel_hi:[1,0]
	v_pk_mul_f32 v[40:41], v[40:41], v[180:181] op_sel_hi:[1,0]
	v_pk_mul_f32 v[36:37], v[36:37], v[182:183] op_sel_hi:[1,0]
	v_pk_mul_f32 v[32:33], v[32:33], v[144:145] op_sel_hi:[1,0]
	s_nop 1
	v_mov_b32_dpp v248, v48 row_shr:1 row_mask:0xf bank_mask:0xf bound_ctrl:1
	v_mov_b32_dpp v249, v49 row_shr:1 row_mask:0xf bank_mask:0xf bound_ctrl:1
	v_mov_b32_dpp v250, v60 row_shl:1 row_mask:0xf bank_mask:0xf bound_ctrl:1
	v_mov_b32_dpp v251, v61 row_shl:1 row_mask:0xf bank_mask:0xf bound_ctrl:1
	v_pk_fma_f32 v[224:225], v[206:207], v[248:249], v[212:213]
	v_pk_fma_f32 v[226:227], v[206:207], v[60:61], v[212:213]
	v_pk_fma_f32 v[228:229], v[206:207], v[56:57], v[212:213]
	v_pk_fma_f32 v[230:231], v[206:207], v[52:53], v[212:213]
	v_pk_fma_f32 v[224:225], v[208:209], v[60:61], v[224:225]
	v_pk_fma_f32 v[226:227], v[208:209], v[56:57], v[226:227]
	v_pk_fma_f32 v[228:229], v[208:209], v[52:53], v[228:229]
	v_pk_fma_f32 v[230:231], v[208:209], v[48:49], v[230:231]
	v_pk_fma_f32 v[224:225], v[210:211], v[56:57], v[224:225]
	v_pk_fma_f32 v[226:227], v[210:211], v[52:53], v[226:227]
	v_pk_fma_f32 v[228:229], v[210:211], v[48:49], v[228:229]
	v_pk_fma_f32 v[230:231], v[210:211], v[250:251], v[230:231]
	s_nop 1
	v_mov_b32_dpp v248, v32 row_shr:1 row_mask:0xf bank_mask:0xf bound_ctrl:1
	v_mov_b32_dpp v249, v33 row_shr:1 row_mask:0xf bank_mask:0xf bound_ctrl:1
	v_mov_b32_dpp v250, v44 row_shl:1 row_mask:0xf bank_mask:0xf bound_ctrl:1
	v_mov_b32_dpp v251, v45 row_shl:1 row_mask:0xf bank_mask:0xf bound_ctrl:1
	v_pk_fma_f32 v[232:233], v[214:215], v[248:249], v[220:221]
	v_pk_fma_f32 v[234:235], v[214:215], v[44:45], v[220:221]
	v_pk_fma_f32 v[236:237], v[214:215], v[40:41], v[220:221]
	v_pk_fma_f32 v[238:239], v[214:215], v[36:37], v[220:221]
	v_pk_fma_f32 v[232:233], v[216:217], v[44:45], v[232:233]
	v_pk_fma_f32 v[234:235], v[216:217], v[40:41], v[234:235]
	v_pk_fma_f32 v[236:237], v[216:217], v[36:37], v[236:237]
	v_pk_fma_f32 v[238:239], v[216:217], v[32:33], v[238:239]
	v_pk_fma_f32 v[232:233], v[218:219], v[40:41], v[232:233]
	v_pk_fma_f32 v[234:235], v[218:219], v[36:37], v[234:235]
	v_pk_fma_f32 v[236:237], v[218:219], v[32:33], v[236:237]
	v_pk_fma_f32 v[238:239], v[218:219], v[250:251], v[238:239]
	v_exp_f32_e64 v240, -v232
	v_exp_f32_e64 v241, -v233
	v_exp_f32_e64 v242, -v234
	v_exp_f32_e64 v243, -v235
	v_exp_f32_e64 v244, -v236
	v_exp_f32_e64 v245, -v237
	v_exp_f32_e64 v246, -v238
	v_exp_f32_e64 v247, -v239
	v_pk_mul_f32 v[224:225], v[224:225], v[232:233]
	v_pk_mul_f32 v[226:227], v[226:227], v[234:235]
	v_pk_mul_f32 v[228:229], v[228:229], v[236:237]
	v_pk_mul_f32 v[230:231], v[230:231], v[238:239]
	v_pk_add_f32 v[240:241], v[240:241], 1.0 op_sel_hi:[1,0]
	v_pk_add_f32 v[242:243], v[242:243], 1.0 op_sel_hi:[1,0]
	v_pk_add_f32 v[244:245], v[244:245], 1.0 op_sel_hi:[1,0]
	v_pk_add_f32 v[246:247], v[246:247], 1.0 op_sel_hi:[1,0]
	v_rcp_f32_e32 v240, v240
	v_rcp_f32_e32 v241, v241
	v_rcp_f32_e32 v242, v242
	v_rcp_f32_e32 v243, v243
	v_rcp_f32_e32 v244, v244
	v_rcp_f32_e32 v245, v245
	v_rcp_f32_e32 v246, v246
	v_rcp_f32_e32 v247, v247
	s_nop 0
	v_pk_mul_f32 v[224:225], v[224:225], v[240:241]
	v_pk_mul_f32 v[226:227], v[226:227], v[242:243]
	v_pk_mul_f32 v[228:229], v[228:229], v[244:245]
	v_pk_mul_f32 v[230:231], v[230:231], v[246:247]
	v_cvt_pk_bf16_f32 v128, v224, v225
	v_cvt_pk_bf16_f32 v132, v226, v227
	v_cvt_pk_bf16_f32 v136, v228, v229
	v_cvt_pk_bf16_f32 v140, v230, v231
	global_load_dwordx4 v[206:209], v172, s[64:65] offset:128
	global_load_dwordx4 v[210:213], v172, s[64:65] offset:144
	global_load_dwordx4 v[214:217], v172, s[64:65] offset:160
	global_load_dwordx4 v[218:221], v172, s[64:65] offset:176
	s_waitcnt vmcnt(4)
	v_pk_mul_f32 v[62:63], v[62:63], v[178:179] op_sel_hi:[1,0]
	v_pk_mul_f32 v[58:59], v[58:59], v[180:181] op_sel_hi:[1,0]
	v_pk_mul_f32 v[54:55], v[54:55], v[182:183] op_sel_hi:[1,0]
	v_pk_mul_f32 v[50:51], v[50:51], v[144:145] op_sel_hi:[1,0]
	v_pk_mul_f32 v[46:47], v[46:47], v[178:179] op_sel_hi:[1,0]
	v_pk_mul_f32 v[42:43], v[42:43], v[180:181] op_sel_hi:[1,0]
	v_pk_mul_f32 v[38:39], v[38:39], v[182:183] op_sel_hi:[1,0]
	v_pk_mul_f32 v[34:35], v[34:35], v[144:145] op_sel_hi:[1,0]
	s_nop 1
	v_mov_b32_dpp v248, v50 row_shr:1 row_mask:0xf bank_mask:0xf bound_ctrl:1
	v_mov_b32_dpp v249, v51 row_shr:1 row_mask:0xf bank_mask:0xf bound_ctrl:1
	v_mov_b32_dpp v250, v62 row_shl:1 row_mask:0xf bank_mask:0xf bound_ctrl:1
	v_mov_b32_dpp v251, v63 row_shl:1 row_mask:0xf bank_mask:0xf bound_ctrl:1
	v_pk_fma_f32 v[224:225], v[190:191], v[248:249], v[196:197]
	v_pk_fma_f32 v[226:227], v[190:191], v[62:63], v[196:197]
	v_pk_fma_f32 v[228:229], v[190:191], v[58:59], v[196:197]
	v_pk_fma_f32 v[230:231], v[190:191], v[54:55], v[196:197]
	v_pk_fma_f32 v[224:225], v[192:193], v[62:63], v[224:225]
	v_pk_fma_f32 v[226:227], v[192:193], v[58:59], v[226:227]
	v_pk_fma_f32 v[228:229], v[192:193], v[54:55], v[228:229]
	v_pk_fma_f32 v[230:231], v[192:193], v[50:51], v[230:231]
	v_pk_fma_f32 v[224:225], v[194:195], v[58:59], v[224:225]
	v_pk_fma_f32 v[226:227], v[194:195], v[54:55], v[226:227]
	v_pk_fma_f32 v[228:229], v[194:195], v[50:51], v[228:229]
	v_pk_fma_f32 v[230:231], v[194:195], v[250:251], v[230:231]
	s_nop 1
	v_mov_b32_dpp v248, v34 row_shr:1 row_mask:0xf bank_mask:0xf bound_ctrl:1
	v_mov_b32_dpp v249, v35 row_shr:1 row_mask:0xf bank_mask:0xf bound_ctrl:1
;     __device__ __forceinline__ void operator()(const f32x4 (&acc)[2][2][4][2], const Unit& u, int wr, int wc, int fr, int fq) const {
;     ...
;                     const int cidx = (4 * n + 2 * jp) * 2;
;                     const f32x4 c0a = ct[cidx], c0b = ct[cidx + 1], c1a = ct[cidx + 2], c1b = ct[cidx + 3];
;                     const f32x2 wv0 = {c0a[0], c1a[0]}, wv1 = {c0a[1], c1a[1]}, wv2 = {c0a[2], c1a[2]}, bv = {c0a[3], c1a[3]};
;                     const f32x2 wg0 = {c0b[0], c1b[0]}, wg1 = {c0b[1], c1b[1]}, wg2 = {c0b[2], c1b[2]}, bg = {c0b[3], c1b[3]};
;                     f32x2 uv[4], ug[4], cv[4];
; #pragma unroll
;                     for (int m = 0; m < 4; ++m) { uv[m] = (f32x2){acc[ai][0][m][n][2 * jp], acc[ai][0][m][n][2 * jp + 1]}; ug[m] = (f32x2){acc[ai][1][m][n][2 * jp], acc[ai][1][m][n][2 * jp + 1]}; }
;                     asm volatile("" : "+v"(uv[0]), "+v"(uv[1]), "+v"(uv[2]), "+v"(uv[3]), "+v"(ug[0]), "+v"(ug[1]), "+v"(ug[2]), "+v"(ug[3]));
;                     {
;                         f32x2 rv[4], lv[4];
; #pragma unroll
;                         for (int m = 0; m < 4; ++m) { uv[m] = uv[m] * rs[m]; rv[m] = (f32x2){dpp_ror1(uv[m][0]), dpp_ror1(uv[m][1])}; lv[m] = (f32x2){dpp_ror15(uv[m][0]), dpp_ror15(uv[m][1])}; }
; #pragma unroll
;                         for (int m = 0; m < 4; ++m) { const f32x2 pv_ = (m > 0 && f0) ? rv[m > 0 ? m - 1 : 0] : rv[m], nv_ = (m < 3 && f15) ? lv[m < 3 ? m + 1 : 3] : lv[m];
;                             cv[m] = bv + wv0 * pv_ + wv1 * uv[m] + wv2 * nv_; }
;                     }
;                     asm volatile("" : "+v"(cv[0]), "+v"(cv[1]), "+v"(cv[2]), "+v"(cv[3]));
;                     {
;                         f32x2 rg[4], lg[4];
; #pragma unroll
;                         for (int m = 0; m < 4; ++m) { ug[m] = ug[m] * rs[m]; rg[m] = (f32x2){dpp_ror1(ug[m][0]), dpp_ror1(ug[m][1])}; lg[m] = (f32x2){dpp_ror15(ug[m][0]), dpp_ror15(ug[m][1])}; }
; #pragma unroll
;                         for (int m = 0; m < 4; ++m) { const f32x2 pg_ = (m > 0 && f0) ? rg[m > 0 ? m - 1 : 0] : rg[m], ng_ = (m < 3 && f15) ? lg[m < 3 ? m + 1 : 3] : lg[m];
;                             const f32x2 cgt = bg + wg0 * pg_ + wg1 * ug[m] + wg2 * ng_;
;                             const f32x2 e = cgt * (-LOG2E);
;                             const f32x2 d = (f32x2){__builtin_amdgcn_exp2f(e[0]), __builtin_amdgcn_exp2f(e[1])} + 1.f;
	v_mov_b32_dpp v250, v46 row_shl:1 row_mask:0xf bank_mask:0xf bound_ctrl:1
	v_mov_b32_dpp v251, v47 row_shl:1 row_mask:0xf bank_mask:0xf bound_ctrl:1
	v_pk_fma_f32 v[232:233], v[198:199], v[248:249], v[204:205]
	v_pk_fma_f32 v[234:235], v[198:199], v[46:47], v[204:205]
	v_pk_fma_f32 v[236:237], v[198:199], v[42:43], v[204:205]
	v_pk_fma_f32 v[238:239], v[198:199], v[38:39], v[204:205]
	v_pk_fma_f32 v[232:233], v[200:201], v[46:47], v[232:233]
	v_pk_fma_f32 v[234:235], v[200:201], v[42:43], v[234:235]
	v_pk_fma_f32 v[236:237], v[200:201], v[38:39], v[236:237]
	v_pk_fma_f32 v[238:239], v[200:201], v[34:35], v[238:239]
	v_pk_fma_f32 v[232:233], v[202:203], v[42:43], v[232:233]
	v_pk_fma_f32 v[234:235], v[202:203], v[38:39], v[234:235]
	v_pk_fma_f32 v[236:237], v[202:203], v[34:35], v[236:237]
	v_pk_fma_f32 v[238:239], v[202:203], v[250:251], v[238:239]
	v_exp_f32_e64 v240, -v232
	v_exp_f32_e64 v241, -v233
	v_exp_f32_e64 v242, -v234
	v_exp_f32_e64 v243, -v235
	v_exp_f32_e64 v244, -v236
	v_exp_f32_e64 v245, -v237
	v_exp_f32_e64 v246, -v238
	v_exp_f32_e64 v247, -v239
	v_pk_mul_f32 v[224:225], v[224:225], v[232:233]
	v_pk_mul_f32 v[226:227], v[226:227], v[234:235]
	v_pk_mul_f32 v[228:229], v[228:229], v[236:237]
	v_pk_mul_f32 v[230:231], v[230:231], v[238:239]
	v_pk_add_f32 v[240:241], v[240:241], 1.0 op_sel_hi:[1,0]
	v_pk_add_f32 v[242:243], v[242:243], 1.0 op_sel_hi:[1,0]
	v_pk_add_f32 v[244:245], v[244:245], 1.0 op_sel_hi:[1,0]
	v_pk_add_f32 v[246:247], v[246:247], 1.0 op_sel_hi:[1,0]
	v_rcp_f32_e32 v240, v240
	v_rcp_f32_e32 v241, v241
	v_rcp_f32_e32 v242, v242
	v_rcp_f32_e32 v243, v243
	v_rcp_f32_e32 v244, v244
	v_rcp_f32_e32 v245, v245
	v_rcp_f32_e32 v246, v246
	v_rcp_f32_e32 v247, v247
	s_nop 0
	v_pk_mul_f32 v[224:225], v[224:225], v[240:241]
	v_pk_mul_f32 v[226:227], v[226:227], v[242:243]
	v_pk_mul_f32 v[228:229], v[228:229], v[244:245]
	v_pk_mul_f32 v[230:231], v[230:231], v[246:247]
	v_cvt_pk_bf16_f32 v129, v224, v225
	v_cvt_pk_bf16_f32 v133, v226, v227
	v_cvt_pk_bf16_f32 v137, v228, v229
	v_cvt_pk_bf16_f32 v141, v230, v231
	global_load_dwordx4 v[190:193], v172, s[64:65] offset:192
	global_load_dwordx4 v[194:197], v172, s[64:65] offset:208
	global_load_dwordx4 v[198:201], v172, s[64:65] offset:224
	global_load_dwordx4 v[202:205], v172, s[64:65] offset:240
	s_waitcnt vmcnt(4)
	v_pk_mul_f32 v[28:29], v[28:29], v[178:179] op_sel_hi:[1,0]
	v_pk_mul_f32 v[24:25], v[24:25], v[180:181] op_sel_hi:[1,0]
	v_pk_mul_f32 v[20:21], v[20:21], v[182:183] op_sel_hi:[1,0]
	v_pk_mul_f32 v[16:17], v[16:17], v[144:145] op_sel_hi:[1,0]
	v_pk_mul_f32 v[12:13], v[12:13], v[178:179] op_sel_hi:[1,0]
	v_pk_mul_f32 v[8:9], v[8:9], v[180:181] op_sel_hi:[1,0]
	v_pk_mul_f32 v[4:5], v[4:5], v[182:183] op_sel_hi:[1,0]
	v_pk_mul_f32 v[0:1], v[0:1], v[144:145] op_sel_hi:[1,0]
	s_nop 1
	v_mov_b32_dpp v248, v16 row_shr:1 row_mask:0xf bank_mask:0xf bound_ctrl:1
	v_mov_b32_dpp v249, v17 row_shr:1 row_mask:0xf bank_mask:0xf bound_ctrl:1
	v_mov_b32_dpp v250, v28 row_shl:1 row_mask:0xf bank_mask:0xf bound_ctrl:1
	v_mov_b32_dpp v251, v29 row_shl:1 row_mask:0xf bank_mask:0xf bound_ctrl:1
	v_pk_fma_f32 v[224:225], v[206:207], v[248:249], v[212:213]
	v_pk_fma_f32 v[226:227], v[206:207], v[28:29], v[212:213]
	v_pk_fma_f32 v[228:229], v[206:207], v[24:25], v[212:213]
	v_pk_fma_f32 v[230:231], v[206:207], v[20:21], v[212:213]
	v_pk_fma_f32 v[224:225], v[208:209], v[28:29], v[224:225]
	v_pk_fma_f32 v[226:227], v[208:209], v[24:25], v[226:227]
	v_pk_fma_f32 v[228:229], v[208:209], v[20:21], v[228:229]
	v_pk_fma_f32 v[230:231], v[208:209], v[16:17], v[230:231]
	v_pk_fma_f32 v[224:225], v[210:211], v[24:25], v[224:225]
	v_pk_fma_f32 v[226:227], v[210:211], v[20:21], v[226:227]
	v_pk_fma_f32 v[228:229], v[210:211], v[16:17], v[228:229]
	v_pk_fma_f32 v[230:231], v[210:211], v[250:251], v[230:231]
	s_nop 1
	v_mov_b32_dpp v248, v0 row_shr:1 row_mask:0xf bank_mask:0xf bound_ctrl:1
	v_mov_b32_dpp v249, v1 row_shr:1 row_mask:0xf bank_mask:0xf bound_ctrl:1
	v_mov_b32_dpp v250, v12 row_shl:1 row_mask:0xf bank_mask:0xf bound_ctrl:1
	v_mov_b32_dpp v251, v13 row_shl:1 row_mask:0xf bank_mask:0xf bound_ctrl:1
	v_pk_fma_f32 v[232:233], v[214:215], v[248:249], v[220:221]
	v_pk_fma_f32 v[234:235], v[214:215], v[12:13], v[220:221]
	v_pk_fma_f32 v[236:237], v[214:215], v[8:9], v[220:221]
	v_pk_fma_f32 v[238:239], v[214:215], v[4:5], v[220:221]
	v_pk_fma_f32 v[232:233], v[216:217], v[12:13], v[232:233]
	v_pk_fma_f32 v[234:235], v[216:217], v[8:9], v[234:235]
	v_pk_fma_f32 v[236:237], v[216:217], v[4:5], v[236:237]
	v_pk_fma_f32 v[238:239], v[216:217], v[0:1], v[238:239]
	v_pk_fma_f32 v[232:233], v[218:219], v[8:9], v[232:233]
	v_pk_fma_f32 v[234:235], v[218:219], v[4:5], v[234:235]
	v_pk_fma_f32 v[236:237], v[218:219], v[0:1], v[236:237]
	v_pk_fma_f32 v[238:239], v[218:219], v[250:251], v[238:239]
	v_exp_f32_e64 v240, -v232
	v_exp_f32_e64 v241, -v233
	v_exp_f32_e64 v242, -v234
	v_exp_f32_e64 v243, -v235
	v_exp_f32_e64 v244, -v236
	v_exp_f32_e64 v245, -v237
	v_exp_f32_e64 v246, -v238
	v_exp_f32_e64 v247, -v239
	v_pk_mul_f32 v[224:225], v[224:225], v[232:233]
	v_pk_mul_f32 v[226:227], v[226:227], v[234:235]
	v_pk_mul_f32 v[228:229], v[228:229], v[236:237]
	v_pk_mul_f32 v[230:231], v[230:231], v[238:239]
	v_pk_add_f32 v[240:241], v[240:241], 1.0 op_sel_hi:[1,0]
	v_pk_add_f32 v[242:243], v[242:243], 1.0 op_sel_hi:[1,0]
	v_pk_add_f32 v[244:245], v[244:245], 1.0 op_sel_hi:[1,0]
	v_pk_add_f32 v[246:247], v[246:247], 1.0 op_sel_hi:[1,0]
	v_rcp_f32_e32 v240, v240
	v_rcp_f32_e32 v241, v241
	v_rcp_f32_e32 v242, v242
	v_rcp_f32_e32 v243, v243
	v_rcp_f32_e32 v244, v244
	v_rcp_f32_e32 v245, v245
	v_rcp_f32_e32 v246, v246
	v_rcp_f32_e32 v247, v247
	s_nop 0
	v_pk_mul_f32 v[224:225], v[224:225], v[240:241]
	v_pk_mul_f32 v[226:227], v[226:227], v[242:243]
	v_pk_mul_f32 v[228:229], v[228:229], v[244:245]
	v_pk_mul_f32 v[230:231], v[230:231], v[246:247]
	v_cvt_pk_bf16_f32 v130, v224, v225
	v_cvt_pk_bf16_f32 v134, v226, v227
	v_cvt_pk_bf16_f32 v138, v228, v229
	v_cvt_pk_bf16_f32 v142, v230, v231
	s_waitcnt vmcnt(0)
; __device__ __forceinline__ unsigned cvtpk(float lo, float hi) { f32x2 v = {lo, hi}; bf16x2_t b = __builtin_convertvector(v, bf16x2_t); return __builtin_bit_cast(unsigned, b); }
; __device__ __forceinline__ float dpp_ror1(float x) { return __builtin_bit_cast(float, __builtin_amdgcn_mov_dpp(__builtin_bit_cast(int, x), 0x121, 0xF, 0xF, true)); }
; __device__ __forceinline__ float dpp_ror15(float x) { return __builtin_bit_cast(float, __builtin_amdgcn_mov_dpp(__builtin_bit_cast(int, x), 0x12F, 0xF, 0xF, true)); }
;     __device__ __forceinline__ void operator()(const f32x4 (&acc)[2][2][4][2], const Unit& u, int wr, int wc, int fr, int fq) const {
;     ...
;                         for (int m = 0; m < 4; ++m) { ug[m] = ug[m] * rs[m]; rg[m] = (f32x2){dpp_ror1(ug[m][0]), dpp_ror1(ug[m][1])}; lg[m] = (f32x2){dpp_ror15(ug[m][0]), dpp_ror15(ug[m][1])}; }
; #pragma unroll
;                         for (int m = 0; m < 4; ++m) { const f32x2 pg_ = (m > 0 && f0) ? rg[m > 0 ? m - 1 : 0] : rg[m], ng_ = (m < 3 && f15) ? lg[m < 3 ? m + 1 : 3] : lg[m];
;                             const f32x2 cgt = bg + wg0 * pg_ + wg1 * ug[m] + wg2 * ng_;
;                             const f32x2 e = cgt * (-LOG2E);
;                             const f32x2 d = (f32x2){__builtin_amdgcn_exp2f(e[0]), __builtin_amdgcn_exp2f(e[1])} + 1.f;
;                             const f32x2 sg = {__builtin_amdgcn_rcpf(d[0]), __builtin_amdgcn_rcpf(d[1])};
;                             const f32x2 ov = cv[m] * cgt * sg;
;                             outw[m][n][jp] = cvtpk(ov[0], ov[1]); }
;                     }
;                     asm volatile("" : "+v"(outw[0][n][jp]), "+v"(outw[1][n][jp]), "+v"(outw[2][n][jp]), "+v"(outw[3][n][jp]) :: "memory"); __builtin_amdgcn_sched_barrier(0);
;                 }
; #pragma unroll
;             for (int m = 0; m < 4; ++m) { const int i = 16 * m + fr, t = tbase + i;
;                 if (i >= 1 && i <= 62 && t < slen) { u32x4 w; w.x = outw[m][0][0]; w.y = outw[m][0][1]; w.z = outw[m][1][0]; w.w = outw[m][1][1];
;                     *(u32x4*)(Gout + (size_t)(seqbase + t) * DFF + 128 * u.pn + 32 * wc + 8 * fq) = w; } }
	v_pk_mul_f32 v[30:31], v[30:31], v[178:179] op_sel_hi:[1,0]
	v_pk_mul_f32 v[26:27], v[26:27], v[180:181] op_sel_hi:[1,0]
	v_pk_mul_f32 v[22:23], v[22:23], v[182:183] op_sel_hi:[1,0]
	v_pk_mul_f32 v[18:19], v[18:19], v[144:145] op_sel_hi:[1,0]
	v_pk_mul_f32 v[14:15], v[14:15], v[178:179] op_sel_hi:[1,0]
	v_pk_mul_f32 v[10:11], v[10:11], v[180:181] op_sel_hi:[1,0]
	v_pk_mul_f32 v[6:7], v[6:7], v[182:183] op_sel_hi:[1,0]
	v_pk_mul_f32 v[2:3], v[2:3], v[144:145] op_sel_hi:[1,0]
	s_nop 1
	v_mov_b32_dpp v248, v18 row_shr:1 row_mask:0xf bank_mask:0xf bound_ctrl:1
	v_mov_b32_dpp v249, v19 row_shr:1 row_mask:0xf bank_mask:0xf bound_ctrl:1
	v_mov_b32_dpp v250, v30 row_shl:1 row_mask:0xf bank_mask:0xf bound_ctrl:1
	v_mov_b32_dpp v251, v31 row_shl:1 row_mask:0xf bank_mask:0xf bound_ctrl:1
	v_pk_fma_f32 v[224:225], v[190:191], v[248:249], v[196:197]
	v_pk_fma_f32 v[226:227], v[190:191], v[30:31], v[196:197]
	v_pk_fma_f32 v[228:229], v[190:191], v[26:27], v[196:197]
	v_pk_fma_f32 v[230:231], v[190:191], v[22:23], v[196:197]
	v_pk_fma_f32 v[224:225], v[192:193], v[30:31], v[224:225]
	v_pk_fma_f32 v[226:227], v[192:193], v[26:27], v[226:227]
	v_pk_fma_f32 v[228:229], v[192:193], v[22:23], v[228:229]
	v_pk_fma_f32 v[230:231], v[192:193], v[18:19], v[230:231]
	v_pk_fma_f32 v[224:225], v[194:195], v[26:27], v[224:225]
	v_pk_fma_f32 v[226:227], v[194:195], v[22:23], v[226:227]
	v_pk_fma_f32 v[228:229], v[194:195], v[18:19], v[228:229]
	v_pk_fma_f32 v[230:231], v[194:195], v[250:251], v[230:231]
	s_nop 1
	v_mov_b32_dpp v248, v2 row_shr:1 row_mask:0xf bank_mask:0xf bound_ctrl:1
	v_mov_b32_dpp v249, v3 row_shr:1 row_mask:0xf bank_mask:0xf bound_ctrl:1
	v_mov_b32_dpp v250, v14 row_shl:1 row_mask:0xf bank_mask:0xf bound_ctrl:1
	v_mov_b32_dpp v251, v15 row_shl:1 row_mask:0xf bank_mask:0xf bound_ctrl:1
	v_pk_fma_f32 v[232:233], v[198:199], v[248:249], v[204:205]
	v_pk_fma_f32 v[234:235], v[198:199], v[14:15], v[204:205]
	v_pk_fma_f32 v[236:237], v[198:199], v[10:11], v[204:205]
	v_pk_fma_f32 v[238:239], v[198:199], v[6:7], v[204:205]
	v_pk_fma_f32 v[232:233], v[200:201], v[14:15], v[232:233]
	v_pk_fma_f32 v[234:235], v[200:201], v[10:11], v[234:235]
	v_pk_fma_f32 v[236:237], v[200:201], v[6:7], v[236:237]
	v_pk_fma_f32 v[238:239], v[200:201], v[2:3], v[238:239]
	v_pk_fma_f32 v[232:233], v[202:203], v[10:11], v[232:233]
	v_pk_fma_f32 v[234:235], v[202:203], v[6:7], v[234:235]
	v_pk_fma_f32 v[236:237], v[202:203], v[2:3], v[236:237]
	v_pk_fma_f32 v[238:239], v[202:203], v[250:251], v[238:239]
	v_exp_f32_e64 v240, -v232
	v_exp_f32_e64 v241, -v233
	v_exp_f32_e64 v242, -v234
	v_exp_f32_e64 v243, -v235
	v_exp_f32_e64 v244, -v236
	v_exp_f32_e64 v245, -v237
	v_exp_f32_e64 v246, -v238
	v_exp_f32_e64 v247, -v239
	v_pk_mul_f32 v[224:225], v[224:225], v[232:233]
	v_pk_mul_f32 v[226:227], v[226:227], v[234:235]
	v_pk_mul_f32 v[228:229], v[228:229], v[236:237]
	v_pk_mul_f32 v[230:231], v[230:231], v[238:239]
	v_pk_add_f32 v[240:241], v[240:241], 1.0 op_sel_hi:[1,0]
	v_pk_add_f32 v[242:243], v[242:243], 1.0 op_sel_hi:[1,0]
	v_pk_add_f32 v[244:245], v[244:245], 1.0 op_sel_hi:[1,0]
	v_pk_add_f32 v[246:247], v[246:247], 1.0 op_sel_hi:[1,0]
	v_rcp_f32_e32 v240, v240
	v_rcp_f32_e32 v241, v241
	v_rcp_f32_e32 v242, v242
	v_rcp_f32_e32 v243, v243
	v_rcp_f32_e32 v244, v244
	v_rcp_f32_e32 v245, v245
	v_rcp_f32_e32 v246, v246
	v_rcp_f32_e32 v247, v247
	s_nop 0
	v_pk_mul_f32 v[224:225], v[224:225], v[240:241]
	v_pk_mul_f32 v[226:227], v[226:227], v[242:243]
	v_pk_mul_f32 v[228:229], v[228:229], v[244:245]
	v_pk_mul_f32 v[230:231], v[230:231], v[246:247]
	v_cvt_pk_bf16_f32 v131, v224, v225
	v_cvt_pk_bf16_f32 v135, v226, v227
	v_cvt_pk_bf16_f32 v139, v228, v229
	v_cvt_pk_bf16_f32 v143, v230, v231
	s_sub_i32 s51, s91, s89
	s_sub_i32 s66, s51, 4
	s_max_i32 s66, s66, 0
	v_add_u32_e32 v176, -4, v164
	v_cmp_gt_u32_e32 vcc, s66, v176
	v_add_u32_e32 v176, 0, v174
	v_add_u32_e32 v176, s88, v176
	v_mad_u32_u24 v248, v176, s54, v165
	s_mov_b64 exec, vcc
	global_store_dwordx4 v248, v[128:131], s[86:87]
	s_mov_b64 exec, -1
	s_sub_i32 s66, s51, 1
	s_max_i32 s66, s66, 0
	v_cmp_gt_u32_e32 vcc, s66, v164
	v_add_u32_e32 v176, 1, v174
	v_add_u32_e32 v176, s88, v176
	v_mad_u32_u24 v249, v176, s54, v165
	s_mov_b64 exec, vcc
	global_store_dwordx4 v249, v[132:135], s[86:87]
	s_mov_b64 exec, -1
	s_sub_i32 s66, s51, 2
	s_max_i32 s66, s66, 0
	v_cmp_gt_u32_e32 vcc, s66, v164
	v_add_u32_e32 v176, 2, v174
	v_add_u32_e32 v176, s88, v176
	v_mad_u32_u24 v250, v176, s54, v165
	s_mov_b64 exec, vcc
	global_store_dwordx4 v250, v[136:139], s[86:87]
	s_mov_b64 exec, -1
	s_sub_i32 s66, s51, 3
	s_min_i32 s66, s66, 60
	s_max_i32 s66, s66, 0
	v_cmp_gt_u32_e32 vcc, s66, v164
	v_add_u32_e32 v176, 3, v174
	v_add_u32_e32 v176, s88, v176
	v_mad_u32_u24 v251, v176, s54, v165
	s_mov_b64 exec, vcc
	global_store_dwordx4 v251, v[140:143], s[86:87]
	s_mov_b64 exec, -1
	s_mov_b64 s[2:3], exec
